# wave reductions (LayerNorm passes, conv LN): xor-1/2/4/8 ds_swizzle steps replaced by DPP adds (quad_perm / row_half_mirror / row_mirror), on the non-GEMM latency stack
# baseline (speedup 1.0000x reference)
; __device__ __forceinline__ void conv_item(int l, int it, LAS unsigned char* lds, const bf16_t* CGB, bf16_t* YC, const float* conv_w, const float* conv_b,
;                                           const float* conv_ln_g, const float* conv_ln_b, int tid, int lane, int wave) {
;     ...
;             for (int ib = 0; ib < 48; ib += 12) {
;                 unsigned raw[12]; const void* pp[12];
; #pragma unroll
;                 for (int j = 0; j < 12; ++j) { const int off = tp - 30 + (ib + j < 46 ? ib + j : 45); pp[j] = CGB + (r0 + (pos0 + off >= 0 ? off : -pos0)) * BW; }
;                 ld_u16_s12(raw, (unsigned)c * 2u, pp);
; #pragma unroll
;                 for (int j = 0; j < 12; ++j) if (ib + j < 46) x[ib + j] = (pos0 + tp - 30 + ib + j >= 0) ? __uint_as_float(raw[j] << 16) : 0.f;
;             }
.LBB0_102:
	s_or_b32 s9, s8, s42
	s_sub_i32 s4, s9, 30
	s_max_i32 s4, s4, s7
	s_ashr_i32 s5, s4, 31
	s_add_u32 s4, s0, s4
	s_addc_u32 s5, s1, s5
	s_lshl_b64 s[4:5], s[4:5], 9
	s_add_u32 s4, s78, s4
	s_addc_u32 s5, s79, s5
	s_sub_i32 s10, s9, 29
	s_max_i32 s10, s10, s7
	s_ashr_i32 s11, s10, 31
	s_add_u32 s10, s0, s10
	s_addc_u32 s11, s1, s11
	s_lshl_b64 s[10:11], s[10:11], 9
	s_add_u32 s12, s78, s10
	s_addc_u32 s13, s79, s11
	s_sub_i32 s10, s9, 28
	s_max_i32 s10, s10, s7
	s_ashr_i32 s11, s10, 31
	s_add_u32 s10, s0, s10
	s_addc_u32 s11, s1, s11
	s_lshl_b64 s[10:11], s[10:11], 9
	s_add_u32 s16, s78, s10
	s_addc_u32 s17, s79, s11
	s_sub_i32 s10, s9, 27
	s_max_i32 s10, s10, s7
	s_ashr_i32 s11, s10, 31
	s_add_u32 s10, s0, s10
	s_addc_u32 s11, s1, s11
	s_lshl_b64 s[10:11], s[10:11], 9
	s_add_u32 s18, s78, s10
	s_addc_u32 s19, s79, s11
	s_sub_i32 s10, s9, 26
	s_max_i32 s10, s10, s7
	s_ashr_i32 s11, s10, 31
	s_add_u32 s10, s0, s10
	s_addc_u32 s11, s1, s11
	s_lshl_b64 s[10:11], s[10:11], 9
	s_add_u32 s20, s78, s10
	s_addc_u32 s21, s79, s11
	s_sub_i32 s10, s9, 25
	s_max_i32 s10, s10, s7
	s_ashr_i32 s11, s10, 31
	s_add_u32 s10, s0, s10
	s_addc_u32 s11, s1, s11
	s_lshl_b64 s[10:11], s[10:11], 9
	s_add_u32 s22, s78, s10
	s_addc_u32 s23, s79, s11
	s_sub_i32 s10, s9, 24
	s_max_i32 s10, s10, s7
	s_ashr_i32 s11, s10, 31
	s_add_u32 s10, s0, s10
	s_addc_u32 s11, s1, s11
	s_lshl_b64 s[10:11], s[10:11], 9
	s_add_u32 s24, s78, s10
	s_addc_u32 s25, s79, s11
	s_sub_i32 s10, s9, 23
	s_max_i32 s10, s10, s7
	s_ashr_i32 s11, s10, 31
	s_add_u32 s10, s0, s10
	s_addc_u32 s11, s1, s11
	s_lshl_b64 s[10:11], s[10:11], 9
	s_add_u32 s26, s78, s10
	s_addc_u32 s27, s79, s11
	s_sub_i32 s10, s9, 22
	s_max_i32 s10, s10, s7
	s_ashr_i32 s11, s10, 31
	s_add_u32 s10, s0, s10
	s_addc_u32 s11, s1, s11
	s_lshl_b64 s[10:11], s[10:11], 9
	s_add_u32 s28, s78, s10
	s_addc_u32 s29, s79, s11
	s_sub_i32 s10, s9, 21
	s_max_i32 s10, s10, s7
	s_ashr_i32 s11, s10, 31
	s_add_u32 s10, s0, s10
	s_addc_u32 s11, s1, s11
	s_lshl_b64 s[10:11], s[10:11], 9
	s_add_u32 s30, s78, s10
	s_addc_u32 s31, s79, s11
	s_sub_i32 s10, s9, 20
	s_max_i32 s10, s10, s7
	s_ashr_i32 s11, s10, 31
	s_add_u32 s10, s0, s10
	s_addc_u32 s11, s1, s11
	s_lshl_b64 s[10:11], s[10:11], 9
	s_add_u32 s34, s78, s10
	s_addc_u32 s35, s79, s11
	s_sub_i32 s10, s9, 19
	s_max_i32 s10, s10, s7
	s_ashr_i32 s11, s10, 31
	s_add_u32 s10, s0, s10
	s_addc_u32 s11, s1, s11
	s_lshl_b64 s[10:11], s[10:11], 9
	s_add_u32 s36, s78, s10
	s_addc_u32 s37, s79, s11
	s_add_i32 s10, s9, s6
	s_nop 4
	global_load_ushort v108, v33, s[4:5]
	global_load_ushort v109, v33, s[12:13]
	global_load_ushort v110, v33, s[16:17]
	global_load_ushort v111, v33, s[18:19]
	global_load_ushort v112, v33, s[20:21]
	global_load_ushort v113, v33, s[22:23]
	global_load_ushort v114, v33, s[24:25]
	global_load_ushort v115, v33, s[26:27]
	global_load_ushort v116, v33, s[28:29]
	global_load_ushort v117, v33, s[30:31]
	global_load_ushort v118, v33, s[34:35]
	global_load_ushort v119, v33, s[36:37]
	s_sub_i32 s98, s9, 30
	s_ashr_i32 s99, s98, 31
	s_add_u32 s98, s0, s98
	s_addc_u32 s99, s1, s99
	s_lshl_b64 s[98:99], s[98:99], 9
	s_add_u32 s98, s78, s98
	s_addc_u32 s99, s79, s99
	s_add_u32 s98, s98, 0x1800
	s_addc_u32 s99, s99, 0
	global_load_ushort v219, v33, s[98:99]
	s_add_u32 s98, s98, 0x200
	s_addc_u32 s99, s99, 0
	global_load_ushort v220, v33, s[98:99]
	s_add_u32 s98, s98, 0x200
	s_addc_u32 s99, s99, 0
	global_load_ushort v221, v33, s[98:99]
	s_add_u32 s98, s98, 0x200
	s_addc_u32 s99, s99, 0
	global_load_ushort v222, v33, s[98:99]
	s_add_u32 s98, s98, 0x200
	s_addc_u32 s99, s99, 0
	global_load_ushort v223, v33, s[98:99]
	s_add_u32 s98, s98, 0x200
	s_addc_u32 s99, s99, 0
	global_load_ushort v224, v33, s[98:99]
	s_add_u32 s98, s98, 0x200
	s_addc_u32 s99, s99, 0
	global_load_ushort v225, v33, s[98:99]
	s_add_u32 s98, s98, 0x200
	s_addc_u32 s99, s99, 0
	global_load_ushort v226, v33, s[98:99]
	s_add_u32 s98, s98, 0x200
	s_addc_u32 s99, s99, 0
	global_load_ushort v227, v33, s[98:99]
	s_add_u32 s98, s98, 0x200
	s_addc_u32 s99, s99, 0
	global_load_ushort v228, v33, s[98:99]
	s_add_u32 s98, s98, 0x200
	s_addc_u32 s99, s99, 0
	global_load_ushort v229, v33, s[98:99]
	s_add_u32 s98, s98, 0x200
	s_addc_u32 s99, s99, 0
	global_load_ushort v230, v33, s[98:99]
	s_waitcnt vmcnt(12)
	s_cmp_gt_i32 s10, 29
	v_lshlrev_b32_e32 v108, 16, v108
	s_cselect_b64 vcc, -1, 0
	s_cmp_gt_i32 s10, 28
	v_lshlrev_b32_e32 v109, 16, v109
	v_cndmask_b32_e32 v108, 0, v108, vcc
	s_cselect_b64 vcc, -1, 0
	s_cmp_gt_i32 s10, 27
	v_lshlrev_b32_e32 v110, 16, v110
	v_lshlrev_b32_e32 v120, 16, v116
	v_lshlrev_b32_e32 v116, 16, v117
	v_lshlrev_b32_e32 v117, 16, v118
	v_lshlrev_b32_e32 v118, 16, v119
	v_cndmask_b32_e32 v119, 0, v109, vcc
	s_cselect_b64 vcc, -1, 0
	s_cmp_gt_i32 s10, 26
	v_lshlrev_b32_e32 v111, 16, v111
	v_cndmask_b32_e32 v121, 0, v110, vcc
	s_cselect_b64 vcc, -1, 0
	s_cmp_gt_i32 s10, 25
	v_lshlrev_b32_e32 v112, 16, v112
	s_waitcnt vmcnt(0)
; __device__ __forceinline__ void conv_item(int l, int it, LAS unsigned char* lds, const bf16_t* CGB, bf16_t* YC, const float* conv_w, const float* conv_b,
;                                           const float* conv_ln_g, const float* conv_ln_b, int tid, int lane, int wave) {
;     ...
;                 for (int j = 0; j < 12; ++j) { const int off = tp - 30 + (ib + j < 46 ? ib + j : 45); pp[j] = CGB + (r0 + (pos0 + off >= 0 ? off : -pos0)) * BW; }
;                 ld_u16_s12(raw, (unsigned)c * 2u, pp);
;     ...
; #pragma unroll
;             for (int t = 0; t < 16; ++t) {
;                 float acc = bias;
; #pragma unroll
;                 for (int j = 0; j < 31; ++j) acc += wd[j] * x[t + j];
;                 cv[(tp + t) * BW + c] = acc;
	v_fma_f32 v108, v0, v108, v106
	v_cndmask_b32_e32 v122, 0, v111, vcc
	s_cselect_b64 vcc, -1, 0
	s_cmp_gt_i32 s10, 24
	v_lshlrev_b32_e32 v113, 16, v113
	v_fma_f32 v109, v0, v119, v106
	v_fmac_f32_e32 v108, v1, v119
	v_cndmask_b32_e32 v119, 0, v112, vcc
	s_cselect_b64 vcc, -1, 0
	s_cmp_gt_i32 s10, 23
	v_lshlrev_b32_e32 v114, 16, v114
	v_fmac_f32_e32 v109, v1, v121
	v_fma_f32 v110, v0, v121, v106
	v_fmac_f32_e32 v108, v2, v121
	v_cndmask_b32_e32 v121, 0, v113, vcc
	s_cselect_b64 vcc, -1, 0
	s_cmp_gt_i32 s10, 22
	v_lshlrev_b32_e32 v115, 16, v115
	v_fmac_f32_e32 v109, v2, v122
	v_fmac_f32_e32 v110, v1, v122
	v_fma_f32 v111, v0, v122, v106
	v_fmac_f32_e32 v108, v3, v122
	v_cndmask_b32_e32 v122, 0, v114, vcc
	s_cselect_b64 vcc, -1, 0
	s_cmp_gt_i32 s10, 21
	v_fmac_f32_e32 v109, v3, v119
	v_fmac_f32_e32 v110, v2, v119
	v_fmac_f32_e32 v111, v1, v119
	v_fma_f32 v112, v0, v119, v106
	v_fmac_f32_e32 v108, v4, v119
	v_cndmask_b32_e32 v119, 0, v115, vcc
	s_cselect_b64 vcc, -1, 0
	s_cmp_gt_i32 s10, 20
	v_fmac_f32_e32 v109, v4, v121
	v_fmac_f32_e32 v110, v3, v121
	v_fmac_f32_e32 v111, v2, v121
	v_fmac_f32_e32 v112, v1, v121
	v_fma_f32 v113, v0, v121, v106
	v_fmac_f32_e32 v108, v5, v121
	v_cndmask_b32_e32 v120, 0, v120, vcc
	s_cselect_b64 vcc, -1, 0
	s_cmp_gt_i32 s10, 19
	v_fmac_f32_e32 v109, v5, v122
	v_fmac_f32_e32 v110, v4, v122
	v_fmac_f32_e32 v111, v3, v122
	v_fmac_f32_e32 v112, v2, v122
	v_fmac_f32_e32 v113, v1, v122
	v_fma_f32 v114, v0, v122, v106
	v_fmac_f32_e32 v108, v6, v122
	v_cndmask_b32_e32 v121, 0, v116, vcc
	s_cselect_b64 vcc, -1, 0
	s_cmp_gt_i32 s10, 18
	v_fmac_f32_e32 v109, v6, v119
	v_fmac_f32_e32 v110, v5, v119
	v_fmac_f32_e32 v111, v4, v119
	v_fmac_f32_e32 v112, v3, v119
	v_fmac_f32_e32 v113, v2, v119
	v_fmac_f32_e32 v114, v1, v119
	v_fma_f32 v115, v0, v119, v106
	v_fmac_f32_e32 v108, v7, v119
	v_cndmask_b32_e32 v119, 0, v117, vcc
	s_cselect_b64 vcc, -1, 0
	s_sub_i32 s4, s9, 18
	s_max_i32 s4, s4, s7
	s_ashr_i32 s5, s4, 31
	s_add_u32 s4, s0, s4
	s_addc_u32 s5, s1, s5
	s_lshl_b64 s[4:5], s[4:5], 9
	s_add_u32 s12, s78, s4
	s_addc_u32 s13, s79, s5
	s_sub_i32 s4, s9, 17
	s_max_i32 s4, s4, s7
	s_ashr_i32 s5, s4, 31
	s_add_u32 s4, s0, s4
	s_addc_u32 s5, s1, s5
	s_lshl_b64 s[4:5], s[4:5], 9
	s_add_u32 s16, s78, s4
	s_addc_u32 s17, s79, s5
	s_add_i32 s4, s9, -16
	s_max_i32 s4, s4, s7
	s_ashr_i32 s5, s4, 31
	s_add_u32 s4, s0, s4
	s_addc_u32 s5, s1, s5
	s_lshl_b64 s[4:5], s[4:5], 9
	s_add_u32 s18, s78, s4
	s_addc_u32 s19, s79, s5
	s_add_i32 s4, s9, -15
	s_max_i32 s4, s4, s7
	s_ashr_i32 s5, s4, 31
	s_add_u32 s4, s0, s4
	s_addc_u32 s5, s1, s5
	s_lshl_b64 s[4:5], s[4:5], 9
	s_add_u32 s20, s78, s4
	s_addc_u32 s21, s79, s5
	s_add_i32 s4, s9, -14
	s_max_i32 s4, s4, s7
	s_ashr_i32 s5, s4, 31
	s_add_u32 s4, s0, s4
	s_addc_u32 s5, s1, s5
	s_lshl_b64 s[4:5], s[4:5], 9
	s_add_u32 s22, s78, s4
	s_addc_u32 s23, s79, s5
	s_add_i32 s4, s9, -13
	s_max_i32 s4, s4, s7
	s_ashr_i32 s5, s4, 31
	s_add_u32 s4, s0, s4
	s_addc_u32 s5, s1, s5
	s_lshl_b64 s[4:5], s[4:5], 9
	s_add_u32 s24, s78, s4
	s_addc_u32 s25, s79, s5
	s_add_i32 s4, s9, -12
	s_max_i32 s4, s4, s7
	s_ashr_i32 s5, s4, 31
	s_add_u32 s4, s0, s4
	s_addc_u32 s5, s1, s5
	s_lshl_b64 s[4:5], s[4:5], 9
	s_add_u32 s26, s78, s4
	s_addc_u32 s27, s79, s5
	s_add_i32 s4, s9, -11
	s_max_i32 s4, s4, s7
	s_ashr_i32 s5, s4, 31
	s_add_u32 s4, s0, s4
	s_addc_u32 s5, s1, s5
	s_lshl_b64 s[4:5], s[4:5], 9
	s_add_u32 s28, s78, s4
	s_addc_u32 s29, s79, s5
	s_add_i32 s4, s9, -10
	s_max_i32 s4, s4, s7
	s_ashr_i32 s5, s4, 31
	s_add_u32 s4, s0, s4
	s_addc_u32 s5, s1, s5
	s_lshl_b64 s[4:5], s[4:5], 9
	s_add_u32 s30, s78, s4
	s_addc_u32 s31, s79, s5
	s_add_i32 s4, s9, -9
	s_max_i32 s4, s4, s7
	s_ashr_i32 s5, s4, 31
	s_add_u32 s4, s0, s4
	s_addc_u32 s5, s1, s5
	s_lshl_b64 s[4:5], s[4:5], 9
	s_add_u32 s34, s78, s4
	s_addc_u32 s35, s79, s5
	s_add_i32 s4, s9, -8
	s_max_i32 s4, s4, s7
	s_ashr_i32 s5, s4, 31
	s_add_u32 s4, s0, s4
	s_addc_u32 s5, s1, s5
	s_lshl_b64 s[4:5], s[4:5], 9
	s_add_u32 s36, s78, s4
	s_addc_u32 s37, s79, s5
	s_add_i32 s4, s9, -7
	s_max_i32 s4, s4, s7
	s_ashr_i32 s5, s4, 31
	s_add_u32 s4, s0, s4
	s_addc_u32 s5, s1, s5
	v_fmac_f32_e32 v109, v7, v120
	v_fmac_f32_e32 v110, v6, v120
	v_fmac_f32_e32 v111, v5, v120
	v_fmac_f32_e32 v112, v4, v120
	v_fmac_f32_e32 v113, v3, v120
	v_fmac_f32_e32 v114, v2, v120
	v_fmac_f32_e32 v115, v1, v120
	v_fma_f32 v116, v0, v120, v106
	v_fmac_f32_e32 v108, v8, v120
	s_lshl_b64 s[4:5], s[4:5], 9
	v_fmac_f32_e32 v109, v8, v121
	v_fmac_f32_e32 v110, v7, v121
	v_fmac_f32_e32 v111, v6, v121
	v_fmac_f32_e32 v112, v5, v121
	v_fmac_f32_e32 v113, v4, v121
	v_fmac_f32_e32 v114, v3, v121
	v_fmac_f32_e32 v115, v2, v121
	v_fmac_f32_e32 v116, v1, v121
	v_fma_f32 v117, v0, v121, v106
	v_fmac_f32_e32 v108, v9, v121
	s_add_u32 s38, s78, s4
	v_cndmask_b32_e32 v120, 0, v118, vcc
	v_fmac_f32_e32 v109, v9, v119
	v_fmac_f32_e32 v110, v8, v119
	v_fmac_f32_e32 v111, v7, v119
	v_fmac_f32_e32 v112, v6, v119
	v_fmac_f32_e32 v113, v5, v119
	v_fmac_f32_e32 v114, v4, v119
	v_fmac_f32_e32 v115, v3, v119
	v_fmac_f32_e32 v116, v2, v119
	v_fmac_f32_e32 v117, v1, v119
	v_fma_f32 v118, v0, v119, v106
	v_fmac_f32_e32 v108, v10, v119
	s_addc_u32 s39, s79, s5
	s_or_b32 s4, s10, 12
	v_fmac_f32_e32 v109, v10, v120
	v_fmac_f32_e32 v110, v9, v120
	v_fmac_f32_e32 v111, v8, v120
	v_fmac_f32_e32 v112, v7, v120
	v_fmac_f32_e32 v113, v6, v120
	v_fmac_f32_e32 v114, v5, v120
	v_fmac_f32_e32 v115, v4, v120
	v_fmac_f32_e32 v116, v3, v120
	v_fmac_f32_e32 v117, v2, v120
	v_fmac_f32_e32 v118, v1, v120
	v_fma_f32 v119, v0, v120, v106
	v_fmac_f32_e32 v108, v11, v120
	s_add_u32 s98, s98, 0x200
	s_addc_u32 s99, s99, 0
	global_load_ushort v231, v33, s[98:99]
	s_add_u32 s98, s98, 0x200
	s_addc_u32 s99, s99, 0
	global_load_ushort v232, v33, s[98:99]
	s_add_u32 s98, s98, 0x200
	s_addc_u32 s99, s99, 0
	global_load_ushort v233, v33, s[98:99]
	s_add_u32 s98, s98, 0x200
	s_addc_u32 s99, s99, 0
	global_load_ushort v236, v33, s[98:99]
	s_add_u32 s98, s98, 0x200
	s_addc_u32 s99, s99, 0
	global_load_ushort v237, v33, s[98:99]
	s_add_u32 s98, s98, 0x200
	s_addc_u32 s99, s99, 0
	global_load_ushort v238, v33, s[98:99]
	s_add_u32 s98, s98, 0x200
	s_addc_u32 s99, s99, 0
	global_load_ushort v239, v33, s[98:99]
	s_add_u32 s98, s98, 0x200
	s_addc_u32 s99, s99, 0
	global_load_ushort v240, v33, s[98:99]
	s_add_u32 s98, s98, 0x200
	s_addc_u32 s99, s99, 0
	global_load_ushort v245, v33, s[98:99]
	s_add_u32 s98, s98, 0x200
	s_addc_u32 s99, s99, 0
	global_load_ushort v246, v33, s[98:99]
	s_add_u32 s98, s98, 0x200
	s_addc_u32 s99, s99, 0
	global_load_ushort v247, v33, s[98:99]
	s_add_u32 s98, s98, 0x200
	s_addc_u32 s99, s99, 0
	global_load_ushort v248, v33, s[98:99]
	s_waitcnt vmcnt(12)
; __device__ __forceinline__ void conv_item(int l, int it, LAS unsigned char* lds, const bf16_t* CGB, bf16_t* YC, const float* conv_w, const float* conv_b,
;                                           const float* conv_ln_g, const float* conv_ln_b, int tid, int lane, int wave) {
;     ...
;                 for (int j = 0; j < 12; ++j) if (ib + j < 46) x[ib + j] = (pos0 + tp - 30 + ib + j >= 0) ? __uint_as_float(raw[j] << 16) : 0.f;
;             }
; #pragma unroll
;             for (int t = 0; t < 16; ++t) {
;                 float acc = bias;
; #pragma unroll
;                 for (int j = 0; j < 31; ++j) acc += wd[j] * x[t + j];
;                 cv[(tp + t) * BW + c] = acc;
	v_mov_b32_e32 v120, v219
	v_mov_b32_e32 v121, v220
	v_mov_b32_e32 v122, v221
	v_mov_b32_e32 v123, v222
	v_mov_b32_e32 v124, v223
	v_mov_b32_e32 v125, v224
	v_mov_b32_e32 v126, v225
	v_mov_b32_e32 v127, v226
	v_mov_b32_e32 v128, v227
	v_mov_b32_e32 v129, v228
	v_mov_b32_e32 v130, v229
	v_mov_b32_e32 v131, v230
	s_cmp_gt_i32 s4, 29
	v_lshlrev_b32_e32 v120, 16, v120
	s_cselect_b64 vcc, -1, 0
	s_cmp_gt_i32 s4, 28
	v_lshlrev_b32_e32 v121, 16, v121
	v_cndmask_b32_e32 v120, 0, v120, vcc
	s_cselect_b64 vcc, -1, 0
	s_cmp_gt_i32 s4, 27
	v_lshlrev_b32_e32 v122, 16, v122
	v_lshlrev_b32_e32 v150, 16, v127
	v_lshlrev_b32_e32 v127, 16, v128
	v_cndmask_b32_e32 v128, 0, v121, vcc
	s_cselect_b64 vcc, -1, 0
	s_cmp_gt_i32 s4, 26
	v_lshlrev_b32_e32 v123, 16, v123
	v_lshlrev_b32_e32 v149, 16, v126
	v_lshlrev_b32_e32 v126, 16, v129
	v_cndmask_b32_e32 v129, 0, v122, vcc
	s_cselect_b64 vcc, -1, 0
	s_cmp_gt_i32 s4, 25
	v_lshlrev_b32_e32 v132, 16, v124
	v_lshlrev_b32_e32 v133, 16, v125
	v_lshlrev_b32_e32 v125, 16, v130
	v_fmac_f32_e32 v108, v35, v120
	v_fmac_f32_e32 v109, v11, v120
	v_fmac_f32_e32 v110, v10, v120
	v_fmac_f32_e32 v111, v9, v120
	v_fmac_f32_e32 v112, v8, v120
	v_fmac_f32_e32 v113, v7, v120
	v_fmac_f32_e32 v114, v6, v120
	v_fmac_f32_e32 v115, v5, v120
	v_fmac_f32_e32 v116, v4, v120
	v_fmac_f32_e32 v117, v3, v120
	v_fmac_f32_e32 v118, v2, v120
	v_fmac_f32_e32 v119, v1, v120
	v_fma_f32 v121, v0, v120, v106
	v_cndmask_b32_e32 v130, 0, v123, vcc
	s_cselect_b64 vcc, -1, 0
	s_cmp_gt_i32 s4, 24
	v_fma_f32 v120, v0, v128, v106
	v_fmac_f32_e32 v108, v86, v128
	v_fmac_f32_e32 v109, v35, v128
	v_fmac_f32_e32 v110, v11, v128
	v_fmac_f32_e32 v111, v10, v128
	v_fmac_f32_e32 v112, v9, v128
	v_fmac_f32_e32 v113, v8, v128
	v_fmac_f32_e32 v114, v7, v128
	v_fmac_f32_e32 v115, v6, v128
	v_fmac_f32_e32 v116, v5, v128
	v_fmac_f32_e32 v117, v4, v128
	v_fmac_f32_e32 v118, v3, v128
	v_fmac_f32_e32 v119, v2, v128
	v_fmac_f32_e32 v121, v1, v128
	v_cndmask_b32_e32 v128, 0, v132, vcc
	s_cselect_b64 vcc, -1, 0
	s_cmp_gt_i32 s4, 23
	v_fmac_f32_e32 v120, v1, v129
	v_fma_f32 v122, v0, v129, v106
	v_fmac_f32_e32 v108, v87, v129
	v_fmac_f32_e32 v109, v86, v129
	v_fmac_f32_e32 v110, v35, v129
	v_fmac_f32_e32 v111, v11, v129
	v_fmac_f32_e32 v112, v10, v129
	v_fmac_f32_e32 v113, v9, v129
	v_fmac_f32_e32 v114, v8, v129
	v_fmac_f32_e32 v115, v7, v129
	v_fmac_f32_e32 v116, v6, v129
	v_fmac_f32_e32 v117, v5, v129
	v_fmac_f32_e32 v118, v4, v129
	v_fmac_f32_e32 v119, v3, v129
	v_fmac_f32_e32 v121, v2, v129
	v_cndmask_b32_e32 v129, 0, v133, vcc
	s_cselect_b64 vcc, -1, 0
	s_cmp_gt_i32 s4, 22
	v_fmac_f32_e32 v120, v2, v130
	v_fmac_f32_e32 v122, v1, v130
	v_fma_f32 v123, v0, v130, v106
	v_fmac_f32_e32 v108, v90, v130
	v_fmac_f32_e32 v109, v87, v130
	v_fmac_f32_e32 v110, v86, v130
	v_fmac_f32_e32 v111, v35, v130
	v_fmac_f32_e32 v112, v11, v130
	v_fmac_f32_e32 v113, v10, v130
	v_fmac_f32_e32 v114, v9, v130
	v_fmac_f32_e32 v115, v8, v130
	v_fmac_f32_e32 v116, v7, v130
	v_fmac_f32_e32 v117, v6, v130
	v_fmac_f32_e32 v118, v5, v130
	v_fmac_f32_e32 v119, v4, v130
	v_fmac_f32_e32 v121, v3, v130
	v_cndmask_b32_e32 v130, 0, v149, vcc
	s_cselect_b64 vcc, -1, 0
	s_cmp_gt_i32 s4, 21
	v_fmac_f32_e32 v120, v3, v128
	v_fmac_f32_e32 v122, v2, v128
	v_fmac_f32_e32 v123, v1, v128
	v_fmac_f32_e32 v108, v91, v128
	v_fmac_f32_e32 v109, v90, v128
	v_fmac_f32_e32 v110, v87, v128
	v_fmac_f32_e32 v111, v86, v128
	v_fmac_f32_e32 v112, v35, v128
	v_fmac_f32_e32 v113, v11, v128
	v_fmac_f32_e32 v114, v10, v128
	v_fmac_f32_e32 v115, v9, v128
	v_fmac_f32_e32 v116, v8, v128
	v_fmac_f32_e32 v117, v7, v128
	v_fmac_f32_e32 v118, v6, v128
	v_fmac_f32_e32 v119, v5, v128
	v_fmac_f32_e32 v121, v4, v128
	v_cndmask_b32_e32 v128, 0, v150, vcc
	s_cselect_b64 vcc, -1, 0
	s_cmp_gt_i32 s4, 20
	v_cndmask_b32_e32 v127, 0, v127, vcc
	s_cselect_b64 vcc, -1, 0
	s_cmp_gt_i32 s4, 19
	v_cndmask_b32_e32 v126, 0, v126, vcc
	s_cselect_b64 vcc, -1, 0
	s_cmp_gt_i32 s4, 18
	v_cndmask_b32_e32 v125, 0, v125, vcc
	s_cselect_b64 vcc, -1, 0
	s_add_i32 s4, s9, -6
	s_max_i32 s4, s4, s7
	s_ashr_i32 s5, s4, 31
	s_add_u32 s4, s0, s4
	s_addc_u32 s5, s1, s5
	s_lshl_b64 s[4:5], s[4:5], 9
	s_add_u32 s4, s78, s4
	s_addc_u32 s5, s79, s5
	s_add_i32 s11, s9, -5
	s_max_i32 s11, s11, s7
	s_ashr_i32 s13, s11, 31
	s_add_u32 s12, s0, s11
	s_addc_u32 s13, s1, s13
	s_lshl_b64 s[12:13], s[12:13], 9
	s_add_u32 s12, s78, s12
	s_addc_u32 s13, s79, s13
	s_add_i32 s11, s9, -4
	s_max_i32 s11, s11, s7
	s_ashr_i32 s14, s11, 31
	s_add_u32 s16, s0, s11
	s_addc_u32 s17, s1, s14
	s_lshl_b64 s[16:17], s[16:17], 9
	s_add_u32 s16, s78, s16
	s_addc_u32 s17, s79, s17
	s_add_i32 s11, s9, -3
	s_max_i32 s11, s11, s7
	s_ashr_i32 s14, s11, 31
	s_add_u32 s18, s0, s11
	s_addc_u32 s19, s1, s14
	s_lshl_b64 s[18:19], s[18:19], 9
	s_add_u32 s18, s78, s18
	s_addc_u32 s19, s79, s19
	s_add_i32 s11, s9, -2
	s_max_i32 s11, s11, s7
	s_ashr_i32 s14, s11, 31
	s_add_u32 s20, s0, s11
	s_addc_u32 s21, s1, s14
	s_lshl_b64 s[20:21], s[20:21], 9
	s_add_u32 s20, s78, s20
	s_addc_u32 s21, s79, s21
	s_add_i32 s11, s9, -1
	s_max_i32 s11, s11, s7
	s_ashr_i32 s14, s11, 31
	s_add_u32 s22, s0, s11
	s_addc_u32 s23, s1, s14
	s_lshl_b64 s[22:23], s[22:23], 9
	s_add_u32 s22, s78, s22
	s_addc_u32 s23, s79, s23
	s_max_i32 s11, s9, s7
	s_ashr_i32 s14, s11, 31
	v_fmac_f32_e32 v120, v4, v129
	v_fmac_f32_e32 v122, v3, v129
	v_fmac_f32_e32 v123, v2, v129
	v_fmac_f32_e32 v108, v92, v129
	v_fmac_f32_e32 v109, v91, v129
	v_fmac_f32_e32 v110, v90, v129
	v_fmac_f32_e32 v111, v87, v129
	v_fmac_f32_e32 v112, v86, v129
	v_fmac_f32_e32 v113, v35, v129
	v_fmac_f32_e32 v114, v11, v129
	v_fmac_f32_e32 v115, v10, v129
	v_fmac_f32_e32 v116, v9, v129
; __device__ __forceinline__ void conv_item(int l, int it, LAS unsigned char* lds, const bf16_t* CGB, bf16_t* YC, const float* conv_w, const float* conv_b,
;                                           const float* conv_ln_g, const float* conv_ln_b, int tid, int lane, int wave) {
;     ...
;                 for (int j = 0; j < 12; ++j) if (ib + j < 46) x[ib + j] = (pos0 + tp - 30 + ib + j >= 0) ? __uint_as_float(raw[j] << 16) : 0.f;
;             }
; #pragma unroll
;             for (int t = 0; t < 16; ++t) {
;                 float acc = bias;
; #pragma unroll
;                 for (int j = 0; j < 31; ++j) acc += wd[j] * x[t + j];
;                 cv[(tp + t) * BW + c] = acc;
	v_fmac_f32_e32 v117, v8, v129
	v_fmac_f32_e32 v118, v7, v129
	v_fmac_f32_e32 v119, v6, v129
	v_fmac_f32_e32 v121, v5, v129
	s_add_u32 s24, s0, s11
	v_fmac_f32_e32 v120, v5, v130
	v_fmac_f32_e32 v122, v4, v130
	v_fmac_f32_e32 v123, v3, v130
	v_fmac_f32_e32 v108, v93, v130
	v_fmac_f32_e32 v109, v92, v130
	v_fmac_f32_e32 v110, v91, v130
	v_fmac_f32_e32 v111, v90, v130
	v_fmac_f32_e32 v112, v87, v130
	v_fmac_f32_e32 v113, v86, v130
	v_fmac_f32_e32 v114, v35, v130
	v_fmac_f32_e32 v115, v11, v130
	v_fmac_f32_e32 v116, v10, v130
	v_fmac_f32_e32 v117, v9, v130
	v_fmac_f32_e32 v118, v8, v130
	v_fmac_f32_e32 v119, v7, v130
	v_fmac_f32_e32 v121, v6, v130
	s_addc_u32 s25, s1, s14
	v_fmac_f32_e32 v120, v6, v128
	v_fmac_f32_e32 v122, v5, v128
	v_fmac_f32_e32 v123, v4, v128
	v_fmac_f32_e32 v108, v94, v128
	v_fmac_f32_e32 v109, v93, v128
	v_fmac_f32_e32 v110, v92, v128
	v_fmac_f32_e32 v111, v91, v128
	v_fmac_f32_e32 v112, v90, v128
	v_fmac_f32_e32 v113, v87, v128
	v_fmac_f32_e32 v114, v86, v128
	v_fmac_f32_e32 v115, v35, v128
	v_fmac_f32_e32 v116, v11, v128
	v_fmac_f32_e32 v117, v10, v128
	v_fmac_f32_e32 v118, v9, v128
	v_fmac_f32_e32 v119, v8, v128
	v_fmac_f32_e32 v121, v7, v128
	s_lshl_b64 s[24:25], s[24:25], 9
	v_fmac_f32_e32 v120, v7, v127
	v_fmac_f32_e32 v122, v6, v127
	v_fmac_f32_e32 v123, v5, v127
	v_fmac_f32_e32 v108, v95, v127
	v_fmac_f32_e32 v109, v94, v127
	v_fmac_f32_e32 v110, v93, v127
	v_fmac_f32_e32 v111, v92, v127
	v_fmac_f32_e32 v112, v91, v127
	v_fmac_f32_e32 v113, v90, v127
	v_fmac_f32_e32 v114, v87, v127
	v_fmac_f32_e32 v115, v86, v127
	v_fmac_f32_e32 v116, v35, v127
	v_fmac_f32_e32 v117, v11, v127
	v_fmac_f32_e32 v118, v10, v127
	v_fmac_f32_e32 v119, v9, v127
	v_fmac_f32_e32 v121, v8, v127
	s_add_u32 s24, s78, s24
	v_lshlrev_b32_e32 v124, 16, v131
	v_fmac_f32_e32 v120, v8, v126
	v_fmac_f32_e32 v122, v7, v126
	v_fmac_f32_e32 v123, v6, v126
	v_fmac_f32_e32 v108, v96, v126
	v_fmac_f32_e32 v109, v95, v126
	v_fmac_f32_e32 v110, v94, v126
	v_fmac_f32_e32 v111, v93, v126
	v_fmac_f32_e32 v112, v92, v126
	v_fmac_f32_e32 v113, v91, v126
	v_fmac_f32_e32 v114, v90, v126
	v_fmac_f32_e32 v115, v87, v126
	v_fmac_f32_e32 v116, v86, v126
	v_fmac_f32_e32 v117, v35, v126
	v_fmac_f32_e32 v118, v11, v126
	v_fmac_f32_e32 v119, v10, v126
	v_fmac_f32_e32 v121, v9, v126
	s_addc_u32 s25, s79, s25
	s_or_b32 s11, s9, 1
	v_cndmask_b32_e32 v124, 0, v124, vcc
	v_fmac_f32_e32 v120, v9, v125
	v_fmac_f32_e32 v122, v8, v125
	v_fmac_f32_e32 v123, v7, v125
	v_fmac_f32_e32 v108, v97, v125
	v_fmac_f32_e32 v109, v96, v125
	v_fmac_f32_e32 v110, v95, v125
	v_fmac_f32_e32 v111, v94, v125
	v_fmac_f32_e32 v112, v93, v125
	v_fmac_f32_e32 v113, v92, v125
	v_fmac_f32_e32 v114, v91, v125
	v_fmac_f32_e32 v115, v90, v125
	v_fmac_f32_e32 v116, v87, v125
	v_fmac_f32_e32 v117, v86, v125
	v_fmac_f32_e32 v118, v35, v125
	v_fmac_f32_e32 v119, v11, v125
	v_fmac_f32_e32 v121, v10, v125
	s_max_i32 s14, s11, s7
	v_fmac_f32_e32 v120, v10, v124
	v_fmac_f32_e32 v122, v9, v124
	v_fmac_f32_e32 v123, v8, v124
	v_fmac_f32_e32 v108, v98, v124
	v_fmac_f32_e32 v109, v97, v124
	v_fmac_f32_e32 v110, v96, v124
	v_fmac_f32_e32 v111, v95, v124
	v_fmac_f32_e32 v112, v94, v124
	v_fmac_f32_e32 v113, v93, v124
	v_fmac_f32_e32 v114, v92, v124
	v_fmac_f32_e32 v115, v91, v124
	v_fmac_f32_e32 v116, v90, v124
	v_fmac_f32_e32 v117, v87, v124
	v_fmac_f32_e32 v118, v86, v124
	v_fmac_f32_e32 v119, v35, v124
	v_fmac_f32_e32 v121, v11, v124
	v_lshl_add_u32 v124, s11, 10, v88
	s_ashr_i32 s11, s14, 31
	s_add_u32 s26, s0, s14
	s_addc_u32 s27, s1, s11
	s_lshl_b64 s[26:27], s[26:27], 9
	s_add_u32 s26, s78, s26
	s_addc_u32 s27, s79, s27
	s_or_b32 s11, s9, 2
	s_max_i32 s14, s11, s7
	v_lshl_add_u32 v125, s11, 10, v88
	s_ashr_i32 s11, s14, 31
	s_add_u32 s28, s0, s14
	s_addc_u32 s29, s1, s11
	s_lshl_b64 s[28:29], s[28:29], 9
	s_add_u32 s28, s78, s28
	s_addc_u32 s29, s79, s29
	s_or_b32 s11, s9, 3
	s_max_i32 s14, s11, s7
	v_lshl_add_u32 v126, s11, 10, v88
	s_ashr_i32 s11, s14, 31
	s_add_u32 s30, s0, s14
	s_addc_u32 s31, s1, s11
	s_lshl_b64 s[30:31], s[30:31], 9
	s_add_u32 s30, s78, s30
	s_addc_u32 s31, s79, s31
	s_or_b32 s11, s9, 4
	s_max_i32 s14, s11, s7
	v_lshl_add_u32 v127, s11, 10, v88
	s_ashr_i32 s11, s14, 31
	s_add_u32 s34, s0, s14
	s_addc_u32 s35, s1, s11
	s_lshl_b64 s[34:35], s[34:35], 9
	s_add_u32 s34, s78, s34
	s_addc_u32 s35, s79, s35
	s_or_b32 s11, s9, 5
	s_max_i32 s14, s11, s7
	v_lshl_add_u32 v128, s11, 10, v88
	s_ashr_i32 s11, s14, 31
	s_add_u32 s36, s0, s14
	s_addc_u32 s37, s1, s11
	s_lshl_b64 s[36:37], s[36:37], 9
	s_add_u32 s36, s78, s36
	s_addc_u32 s37, s79, s37
	s_add_u32 s98, s98, 0x200
	s_addc_u32 s99, s99, 0
	global_load_ushort v219, v33, s[98:99]
	s_add_u32 s98, s98, 0x200
	s_addc_u32 s99, s99, 0
	global_load_ushort v220, v33, s[98:99]
	s_add_u32 s98, s98, 0x200
	s_addc_u32 s99, s99, 0
	global_load_ushort v221, v33, s[98:99]
	s_add_u32 s98, s98, 0x200
	s_addc_u32 s99, s99, 0
	global_load_ushort v222, v33, s[98:99]
	s_add_u32 s98, s98, 0x200
	s_addc_u32 s99, s99, 0
	global_load_ushort v223, v33, s[98:99]
	s_add_u32 s98, s98, 0x200
	s_addc_u32 s99, s99, 0
	global_load_ushort v224, v33, s[98:99]
	s_add_u32 s98, s98, 0x200
	s_addc_u32 s99, s99, 0
	global_load_ushort v225, v33, s[98:99]
	s_add_u32 s98, s98, 0x200
	s_addc_u32 s99, s99, 0
	global_load_ushort v226, v33, s[98:99]
	s_add_u32 s98, s98, 0x200
	s_addc_u32 s99, s99, 0
	global_load_ushort v227, v33, s[98:99]
	s_add_u32 s98, s98, 0x200
	s_addc_u32 s99, s99, 0
	global_load_ushort v228, v33, s[98:99]
	global_load_ushort v229, v33, s[98:99]
	global_load_ushort v230, v33, s[98:99]
	s_waitcnt vmcnt(12)
; __device__ __forceinline__ void conv_item(int l, int it, LAS unsigned char* lds, const bf16_t* CGB, bf16_t* YC, const float* conv_w, const float* conv_b,
;                                           const float* conv_ln_g, const float* conv_ln_b, int tid, int lane, int wave) {
;     ...
;                 for (int j = 0; j < 12; ++j) if (ib + j < 46) x[ib + j] = (pos0 + tp - 30 + ib + j >= 0) ? __uint_as_float(raw[j] << 16) : 0.f;
;             }
; #pragma unroll
;             for (int t = 0; t < 16; ++t) {
;                 float acc = bias;
; #pragma unroll
;                 for (int j = 0; j < 31; ++j) acc += wd[j] * x[t + j];
;                 cv[(tp + t) * BW + c] = acc;
	v_mov_b32_e32 v129, v231
	v_mov_b32_e32 v130, v232
	v_mov_b32_e32 v131, v233
	v_mov_b32_e32 v132, v236
	v_mov_b32_e32 v133, v237
	v_mov_b32_e32 v149, v238
	v_mov_b32_e32 v150, v239
	v_mov_b32_e32 v151, v240
	v_mov_b32_e32 v152, v245
	v_mov_b32_e32 v153, v246
	v_mov_b32_e32 v154, v247
	v_mov_b32_e32 v155, v248
	s_cmp_gt_i32 s10, 5
	v_lshlrev_b32_e32 v129, 16, v129
	s_cselect_b64 vcc, -1, 0
	s_cmp_gt_i32 s10, 4
	v_lshlrev_b32_e32 v130, 16, v130
	v_cndmask_b32_e32 v129, 0, v129, vcc
	s_cselect_b64 vcc, -1, 0
	s_cmp_gt_i32 s10, 3
	v_lshlrev_b32_e32 v131, 16, v131
	v_cndmask_b32_e32 v130, 0, v130, vcc
	s_cselect_b64 vcc, -1, 0
	s_cmp_gt_i32 s10, 2
	v_lshlrev_b32_e32 v132, 16, v132
	v_cndmask_b32_e32 v131, 0, v131, vcc
	s_cselect_b64 vcc, -1, 0
	s_cmp_gt_i32 s10, 1
	v_lshlrev_b32_e32 v133, 16, v133
	v_fmac_f32_e32 v108, v99, v129
	v_fmac_f32_e32 v109, v98, v129
	v_fmac_f32_e32 v110, v97, v129
	v_fmac_f32_e32 v111, v96, v129
	v_fmac_f32_e32 v112, v95, v129
	v_fmac_f32_e32 v113, v94, v129
	v_fmac_f32_e32 v114, v93, v129
	v_fmac_f32_e32 v115, v92, v129
	v_fmac_f32_e32 v116, v91, v129
	v_fmac_f32_e32 v117, v90, v129
	v_fmac_f32_e32 v118, v87, v129
	v_fmac_f32_e32 v119, v86, v129
	v_fmac_f32_e32 v121, v35, v129
	v_fmac_f32_e32 v120, v11, v129
	v_fmac_f32_e32 v122, v10, v129
	v_fmac_f32_e32 v123, v9, v129
	v_cndmask_b32_e32 v129, 0, v132, vcc
	s_cselect_b64 vcc, -1, 0
	s_cmp_gt_i32 s10, 0
	v_lshlrev_b32_e32 v149, 16, v149
	v_fmac_f32_e32 v108, v100, v130
	v_fmac_f32_e32 v109, v99, v130
	v_fmac_f32_e32 v110, v98, v130
	v_fmac_f32_e32 v111, v97, v130
	v_fmac_f32_e32 v112, v96, v130
	v_fmac_f32_e32 v113, v95, v130
	v_fmac_f32_e32 v114, v94, v130
	v_fmac_f32_e32 v115, v93, v130
	v_fmac_f32_e32 v116, v92, v130
	v_fmac_f32_e32 v117, v91, v130
	v_fmac_f32_e32 v118, v90, v130
	v_fmac_f32_e32 v119, v87, v130
	v_fmac_f32_e32 v121, v86, v130
	v_fmac_f32_e32 v120, v35, v130
	v_fmac_f32_e32 v122, v11, v130
	v_fmac_f32_e32 v123, v10, v130
	v_cndmask_b32_e32 v130, 0, v133, vcc
	s_cselect_b64 vcc, -1, 0
	s_cmp_gt_i32 s10, -1
	v_lshlrev_b32_e32 v150, 16, v150
	v_fmac_f32_e32 v108, v101, v131
	v_fmac_f32_e32 v109, v100, v131
	v_fmac_f32_e32 v110, v99, v131
	v_fmac_f32_e32 v111, v98, v131
	v_fmac_f32_e32 v112, v97, v131
	v_fmac_f32_e32 v113, v96, v131
	v_fmac_f32_e32 v114, v95, v131
	v_fmac_f32_e32 v115, v94, v131
	v_fmac_f32_e32 v116, v93, v131
	v_fmac_f32_e32 v117, v92, v131
	v_fmac_f32_e32 v118, v91, v131
	v_fmac_f32_e32 v119, v90, v131
	v_fmac_f32_e32 v121, v87, v131
	v_fmac_f32_e32 v120, v86, v131
	v_fmac_f32_e32 v122, v35, v131
	v_fmac_f32_e32 v123, v11, v131
	v_cndmask_b32_e32 v131, 0, v149, vcc
	s_cselect_b64 vcc, -1, 0
	s_cmp_gt_i32 s10, -2
	v_lshlrev_b32_e32 v151, 16, v151
	v_fmac_f32_e32 v108, v102, v129
	v_fmac_f32_e32 v109, v101, v129
	v_fmac_f32_e32 v110, v100, v129
	v_fmac_f32_e32 v111, v99, v129
	v_fmac_f32_e32 v112, v98, v129
	v_fmac_f32_e32 v113, v97, v129
	v_fmac_f32_e32 v114, v96, v129
	v_fmac_f32_e32 v115, v95, v129
	v_fmac_f32_e32 v116, v94, v129
	v_fmac_f32_e32 v117, v93, v129
	v_fmac_f32_e32 v118, v92, v129
	v_fmac_f32_e32 v119, v91, v129
	v_fmac_f32_e32 v121, v90, v129
	v_fmac_f32_e32 v120, v87, v129
	v_fmac_f32_e32 v122, v86, v129
	v_fmac_f32_e32 v123, v35, v129
	v_cndmask_b32_e32 v129, 0, v150, vcc
	s_cselect_b64 vcc, -1, 0
	s_cmp_gt_i32 s10, -3
	v_lshlrev_b32_e32 v152, 16, v152
	v_fmac_f32_e32 v108, v103, v130
	v_fmac_f32_e32 v109, v102, v130
	v_fmac_f32_e32 v110, v101, v130
	v_fmac_f32_e32 v111, v100, v130
	v_fmac_f32_e32 v112, v99, v130
	v_fmac_f32_e32 v113, v98, v130
	v_fmac_f32_e32 v114, v97, v130
	v_fmac_f32_e32 v115, v96, v130
	v_fmac_f32_e32 v116, v95, v130
	v_fmac_f32_e32 v117, v94, v130
	v_fmac_f32_e32 v118, v93, v130
	v_fmac_f32_e32 v119, v92, v130
	v_fmac_f32_e32 v121, v91, v130
	v_fmac_f32_e32 v120, v90, v130
	v_fmac_f32_e32 v122, v87, v130
	v_fmac_f32_e32 v123, v86, v130
	v_cndmask_b32_e32 v130, 0, v151, vcc
	s_cselect_b64 vcc, -1, 0
	s_cmp_gt_i32 s10, -4
	v_lshlrev_b32_e32 v153, 16, v153
	v_fmac_f32_e32 v108, v104, v131
	v_fmac_f32_e32 v109, v103, v131
	v_fmac_f32_e32 v110, v102, v131
	v_fmac_f32_e32 v111, v101, v131
	v_fmac_f32_e32 v112, v100, v131
	v_fmac_f32_e32 v113, v99, v131
	v_fmac_f32_e32 v114, v98, v131
	v_fmac_f32_e32 v115, v97, v131
	v_fmac_f32_e32 v116, v96, v131
	v_fmac_f32_e32 v117, v95, v131
	v_fmac_f32_e32 v118, v94, v131
	v_fmac_f32_e32 v119, v93, v131
	v_fmac_f32_e32 v121, v92, v131
	v_fmac_f32_e32 v120, v91, v131
	v_fmac_f32_e32 v122, v90, v131
	v_fmac_f32_e32 v123, v87, v131
	v_cndmask_b32_e32 v131, 0, v152, vcc
	s_cselect_b64 vcc, -1, 0
	s_cmp_gt_i32 s10, -5
	v_lshlrev_b32_e32 v154, 16, v154
	v_fmac_f32_e32 v108, v105, v129
	v_fmac_f32_e32 v109, v104, v129
	v_fmac_f32_e32 v110, v103, v129
	v_fmac_f32_e32 v111, v102, v129
	v_fmac_f32_e32 v112, v101, v129
	v_fmac_f32_e32 v113, v100, v129
	v_fmac_f32_e32 v114, v99, v129
	v_fmac_f32_e32 v115, v98, v129
	v_fmac_f32_e32 v116, v97, v129
	v_fmac_f32_e32 v117, v96, v129
	v_fmac_f32_e32 v118, v95, v129
	v_fmac_f32_e32 v119, v94, v129
	v_fmac_f32_e32 v121, v93, v129
	v_fmac_f32_e32 v120, v92, v129
	v_fmac_f32_e32 v122, v91, v129
	v_fmac_f32_e32 v123, v90, v129
	v_cndmask_b32_e32 v129, 0, v153, vcc
	s_cselect_b64 vcc, -1, 0
	s_cmp_gt_i32 s10, -6
	v_fmac_f32_e32 v109, v105, v130
	v_fmac_f32_e32 v110, v104, v130
	v_fmac_f32_e32 v111, v103, v130
	v_fmac_f32_e32 v112, v102, v130
	v_fmac_f32_e32 v113, v101, v130
	v_fmac_f32_e32 v114, v100, v130
	v_fmac_f32_e32 v115, v99, v130
	v_fmac_f32_e32 v116, v98, v130
	v_fmac_f32_e32 v117, v97, v130
	v_fmac_f32_e32 v118, v96, v130
	v_fmac_f32_e32 v119, v95, v130
	v_fmac_f32_e32 v121, v94, v130
	v_fmac_f32_e32 v120, v93, v130
; __device__ __forceinline__ void conv_item(int l, int it, LAS unsigned char* lds, const bf16_t* CGB, bf16_t* YC, const float* conv_w, const float* conv_b,
;                                           const float* conv_ln_g, const float* conv_ln_b, int tid, int lane, int wave) {
;     ...
; #pragma unroll
;             for (int t = 0; t < 16; ++t) {
;                 float acc = bias;
; #pragma unroll
;                 for (int j = 0; j < 31; ++j) acc += wd[j] * x[t + j];
;                 cv[(tp + t) * BW + c] = acc;
	v_fmac_f32_e32 v122, v92, v130
	v_fmac_f32_e32 v123, v91, v130
	v_cndmask_b32_e32 v130, 0, v154, vcc
	s_cselect_b64 vcc, -1, 0
	s_or_b32 s4, s9, 6
	s_max_i32 s5, s4, s7
	v_fmac_f32_e32 v111, v104, v131
	v_fmac_f32_e32 v112, v103, v131
	v_fmac_f32_e32 v113, v102, v131
	v_fmac_f32_e32 v114, v101, v131
	v_fmac_f32_e32 v115, v100, v131
	v_fmac_f32_e32 v116, v99, v131
	v_fmac_f32_e32 v117, v98, v131
	v_fmac_f32_e32 v118, v97, v131
	v_fmac_f32_e32 v119, v96, v131
	v_fmac_f32_e32 v121, v95, v131
	v_fmac_f32_e32 v120, v94, v131
	v_fmac_f32_e32 v122, v93, v131
	v_fmac_f32_e32 v123, v92, v131
	s_ashr_i32 s11, s5, 31
	v_fmac_f32_e32 v111, v105, v129
	v_fmac_f32_e32 v112, v104, v129
	v_fmac_f32_e32 v113, v103, v129
	v_fmac_f32_e32 v114, v102, v129
	v_fmac_f32_e32 v115, v101, v129
	v_fmac_f32_e32 v116, v100, v129
	v_fmac_f32_e32 v117, v99, v129
	v_fmac_f32_e32 v118, v98, v129
	v_fmac_f32_e32 v119, v97, v129
	v_fmac_f32_e32 v121, v96, v129
	v_fmac_f32_e32 v120, v95, v129
	v_fmac_f32_e32 v122, v94, v129
	v_fmac_f32_e32 v123, v93, v129
	v_lshl_add_u32 v129, s4, 10, v88
	s_add_u32 s4, s0, s5
	s_addc_u32 s5, s1, s11
	s_lshl_b64 s[4:5], s[4:5], 9
	s_add_u32 s4, s78, s4
	s_addc_u32 s5, s79, s5
	s_or_b32 s11, s9, 7
	s_max_i32 s12, s11, s7
	v_fmac_f32_e32 v112, v105, v130
	v_fmac_f32_e32 v113, v104, v130
	v_fmac_f32_e32 v114, v103, v130
	v_fmac_f32_e32 v115, v102, v130
	v_fmac_f32_e32 v116, v101, v130
	v_fmac_f32_e32 v117, v100, v130
	v_fmac_f32_e32 v118, v99, v130
	v_fmac_f32_e32 v119, v98, v130
	v_fmac_f32_e32 v121, v97, v130
	v_fmac_f32_e32 v120, v96, v130
	v_fmac_f32_e32 v122, v95, v130
	v_fmac_f32_e32 v123, v94, v130
	v_lshl_add_u32 v130, s11, 10, v88
	s_ashr_i32 s11, s12, 31
	s_add_u32 s12, s0, s12
	s_addc_u32 s13, s1, s11
	s_lshl_b64 s[12:13], s[12:13], 9
	s_add_u32 s12, s78, s12
	v_lshlrev_b32_e32 v155, 16, v155
	s_addc_u32 s13, s79, s13
	s_or_b32 s11, s9, 8
	v_fmac_f32_e32 v110, v105, v131
	v_cndmask_b32_e32 v131, 0, v155, vcc
	s_max_i32 s14, s11, s7
	v_fmac_f32_e32 v113, v105, v131
	v_fmac_f32_e32 v114, v104, v131
	v_fmac_f32_e32 v115, v103, v131
	v_fmac_f32_e32 v116, v102, v131
	v_fmac_f32_e32 v117, v101, v131
	v_fmac_f32_e32 v118, v100, v131
	v_fmac_f32_e32 v119, v99, v131
	v_fmac_f32_e32 v121, v98, v131
	v_fmac_f32_e32 v120, v97, v131
	v_fmac_f32_e32 v122, v96, v131
	v_fmac_f32_e32 v123, v95, v131
	v_lshl_add_u32 v131, s11, 10, v88
	s_ashr_i32 s11, s14, 31
	s_add_u32 s16, s0, s14
	s_addc_u32 s17, s1, s11
	s_lshl_b64 s[16:17], s[16:17], 9
	s_add_u32 s16, s78, s16
	s_addc_u32 s17, s79, s17
	s_or_b32 s11, s9, 9
	s_max_i32 s14, s11, s7
	v_lshl_add_u32 v132, s11, 10, v88
	s_ashr_i32 s11, s14, 31
	s_add_u32 s18, s0, s14
	s_addc_u32 s19, s1, s11
	s_lshl_b64 s[18:19], s[18:19], 9
	s_add_u32 s18, s78, s18
	s_addc_u32 s19, s79, s19
	s_or_b32 s11, s9, 10
	s_max_i32 s14, s11, s7
	v_lshl_add_u32 v133, s11, 10, v88
	s_ashr_i32 s11, s14, 31
	s_add_u32 s20, s0, s14
	s_addc_u32 s21, s1, s11
	s_lshl_b64 s[20:21], s[20:21], 9
	s_add_u32 s20, s78, s20
	s_addc_u32 s21, s79, s21
	s_or_b32 s11, s9, 11
	s_max_i32 s14, s11, s7
	v_lshl_add_u32 v149, s11, 10, v88
	s_ashr_i32 s11, s14, 31
	s_add_u32 s22, s0, s14
	s_addc_u32 s23, s1, s11
	s_lshl_b64 s[22:23], s[22:23], 9
	s_add_u32 s22, s78, s22
	s_addc_u32 s23, s79, s23
	s_or_b32 s11, s9, 12
	s_max_i32 s14, s11, s7
	v_lshl_add_u32 v150, s11, 10, v88
	s_ashr_i32 s11, s14, 31
	s_add_u32 s24, s0, s14
	s_addc_u32 s25, s1, s11
	s_lshl_b64 s[24:25], s[24:25], 9
	s_add_u32 s24, s78, s24
	s_addc_u32 s25, s79, s25
	s_or_b32 s11, s9, 13
	s_max_i32 s14, s11, s7
	v_lshl_add_u32 v151, s11, 10, v88
	s_ashr_i32 s11, s14, 31
	s_add_u32 s26, s0, s14
	s_addc_u32 s27, s1, s11
	s_lshl_b64 s[26:27], s[26:27], 9
	s_add_u32 s26, s78, s26
	s_addc_u32 s27, s79, s27
	s_or_b32 s11, s9, 14
	s_max_i32 s14, s11, s7
	v_lshl_add_u32 v152, s11, 10, v88
	s_ashr_i32 s11, s14, 31
	s_add_u32 s28, s0, s14
	s_addc_u32 s29, s1, s11
	s_lshl_b64 s[28:29], s[28:29], 9
	s_add_u32 s28, s78, s28
	v_lshl_add_u32 v107, s9, 10, v88
	s_addc_u32 s29, s79, s29
	s_or_b32 s9, s9, 15
	s_max_i32 s11, s9, s7
	v_lshl_add_u32 v153, s9, 10, v88
	s_ashr_i32 s9, s11, 31
	s_add_u32 s30, s0, s11
	s_addc_u32 s31, s1, s9
	s_lshl_b64 s[30:31], s[30:31], 9
	s_add_u32 s30, s78, s30
	s_addc_u32 s31, s79, s31
	s_cmp_gt_i32 s10, -7
	s_waitcnt vmcnt(0)
; #define LAS __attribute__((address_space(3)))
; __device__ __forceinline__ unsigned cvt_pk_bf16(float lo, float hi) { unsigned r; asm volatile("v_cvt_pk_bf16_f32 %0, %1, %2" : "=v"(r) : "v"(lo), "v"(hi)); return r; }
; __device__ __forceinline__ float silu_f(float x) { return x * sigmoid_f(x); }
; __device__ __forceinline__ float ln_eps_s() { float e = LN_EPS; asm volatile("" : "+s"(e)); return e; }
; __device__ __forceinline__ void conv_item(int l, int it, LAS unsigned char* lds, const bf16_t* CGB, bf16_t* YC, const float* conv_w, const float* conv_b,
;                                           const float* conv_ln_g, const float* conv_ln_b, int tid, int lane, int wave) {
;     ...
;                 for (int j = 0; j < 12; ++j) if (ib + j < 46) x[ib + j] = (pos0 + tp - 30 + ib + j >= 0) ? __uint_as_float(raw[j] << 16) : 0.f;
;             }
; #pragma unroll
;             for (int t = 0; t < 16; ++t) {
;                 float acc = bias;
; #pragma unroll
;                 for (int j = 0; j < 31; ++j) acc += wd[j] * x[t + j];
;                 cv[(tp + t) * BW + c] = acc;
;             }
;         }
;     }
;     __syncthreads();
;     {
;         const f32x4 gg = *(const f32x4*)(conv_ln_g + l * BW + lane * 4), bb = *(const f32x4*)(conv_ln_b + l * BW + lane * 4);
;         for (int i = 0; i < 8; ++i) {
;             const int row = wave * 8 + i;
;             f32x4 v = *(const LAS f32x4*)(cv + row * BW + lane * 4);
;             const float mean = wave_sum((v.x + v.y) + (v.z + v.w)) * (1.f / BW);
;             v = v - mean;
;             const float rstd = __builtin_amdgcn_rsqf(wave_sum((v.x * v.x + v.y * v.y) + (v.z * v.z + v.w * v.w)) * (1.f / BW) + ln_eps_s());
;             const f32x4 y = v * rstd * gg + bb;
;             u32x2 w; w.x = cvt_pk_bf16(silu_f(y.x), silu_f(y.y)); w.y = cvt_pk_bf16(silu_f(y.z), silu_f(y.w));
;             *(u32x2*)(YC + (size_t)3 * MTOK * BW + (r0 + row) * BW + lane * 4) = w;
	v_mov_b32_e32 v154, v219
	v_mov_b32_e32 v155, v220
	v_mov_b32_e32 v157, v221
	v_mov_b32_e32 v161, v222
	v_mov_b32_e32 v162, v223
	v_mov_b32_e32 v163, v224
	v_mov_b32_e32 v164, v225
	v_mov_b32_e32 v165, v226
	v_mov_b32_e32 v166, v227
	v_mov_b32_e32 v167, v228
	v_mov_b32_e32 v168, v229
	v_mov_b32_e32 v169, v230
	ds_write_b32 v107, v108
	ds_write_b32 v124, v109
	ds_write_b32 v125, v110
	ds_write_b32 v126, v111
	ds_write_b32 v127, v112
	ds_write_b32 v128, v113
	v_lshlrev_b32_e32 v107, 16, v154
	s_cselect_b64 vcc, -1, 0
	s_cmp_gt_i32 s10, -8
	v_lshlrev_b32_e32 v108, 16, v155
	v_cndmask_b32_e32 v107, 0, v107, vcc
	s_cselect_b64 vcc, -1, 0
	s_cmp_gt_i32 s10, -9
	v_lshlrev_b32_e32 v109, 16, v157
	v_cndmask_b32_e32 v108, 0, v108, vcc
	s_cselect_b64 vcc, -1, 0
	s_cmp_gt_i32 s10, -10
	v_fmac_f32_e32 v123, v96, v107
	v_lshlrev_b32_e32 v110, 16, v161
	v_cndmask_b32_e32 v109, 0, v109, vcc
	v_fmac_f32_e32 v122, v97, v107
	s_cselect_b64 vcc, -1, 0
	s_cmp_gt_i32 s10, -11
	v_fmac_f32_e32 v123, v97, v108
	v_lshlrev_b32_e32 v111, 16, v162
	v_fmac_f32_e32 v114, v105, v107
	v_fmac_f32_e32 v115, v104, v107
	v_fmac_f32_e32 v116, v103, v107
	v_fmac_f32_e32 v117, v102, v107
	v_fmac_f32_e32 v118, v101, v107
	v_fmac_f32_e32 v119, v100, v107
	v_fmac_f32_e32 v121, v99, v107
	v_fmac_f32_e32 v120, v98, v107
	v_cndmask_b32_e32 v107, 0, v110, vcc
	v_fmac_f32_e32 v122, v98, v108
	s_cselect_b64 vcc, -1, 0
	s_cmp_gt_i32 s10, -12
	v_fmac_f32_e32 v123, v98, v109
	v_lshlrev_b32_e32 v112, 16, v163
	v_fmac_f32_e32 v115, v105, v108
	v_fmac_f32_e32 v116, v104, v108
	v_fmac_f32_e32 v117, v103, v108
	v_fmac_f32_e32 v118, v102, v108
	v_fmac_f32_e32 v119, v101, v108
	v_fmac_f32_e32 v121, v100, v108
	v_fmac_f32_e32 v120, v99, v108
	v_cndmask_b32_e32 v108, 0, v111, vcc
	v_fmac_f32_e32 v122, v99, v109
	s_cselect_b64 vcc, -1, 0
	s_cmp_gt_i32 s10, -13
	v_fmac_f32_e32 v123, v99, v107
	v_lshlrev_b32_e32 v113, 16, v164
	v_fmac_f32_e32 v116, v105, v109
	v_fmac_f32_e32 v117, v104, v109
	v_fmac_f32_e32 v118, v103, v109
	v_fmac_f32_e32 v119, v102, v109
	v_fmac_f32_e32 v121, v101, v109
	v_fmac_f32_e32 v120, v100, v109
	v_cndmask_b32_e32 v109, 0, v112, vcc
	v_fmac_f32_e32 v122, v100, v107
	s_cselect_b64 vcc, -1, 0
	s_cmp_gt_i32 s10, -14
	v_fmac_f32_e32 v123, v100, v108
	v_lshlrev_b32_e32 v124, 16, v165
	v_fmac_f32_e32 v117, v105, v107
	v_fmac_f32_e32 v118, v104, v107
	v_fmac_f32_e32 v119, v103, v107
	v_fmac_f32_e32 v121, v102, v107
	v_fmac_f32_e32 v120, v101, v107
	v_cndmask_b32_e32 v107, 0, v113, vcc
	v_fmac_f32_e32 v122, v101, v108
	s_cselect_b64 vcc, -1, 0
	s_cmp_gt_i32 s10, -15
	v_fmac_f32_e32 v123, v101, v109
	v_lshlrev_b32_e32 v125, 16, v166
	v_fmac_f32_e32 v118, v105, v108
	v_fmac_f32_e32 v119, v104, v108
	v_fmac_f32_e32 v121, v103, v108
	v_fmac_f32_e32 v120, v102, v108
	v_cndmask_b32_e32 v108, 0, v124, vcc
	v_fmac_f32_e32 v122, v102, v109
	s_cselect_b64 vcc, -1, 0
	s_cmp_gt_i32 s10, -16
	v_fmac_f32_e32 v123, v102, v107
	v_lshlrev_b32_e32 v126, 16, v167
	v_fmac_f32_e32 v119, v105, v109
	v_fmac_f32_e32 v121, v104, v109
	v_fmac_f32_e32 v120, v103, v109
	v_cndmask_b32_e32 v109, 0, v125, vcc
	v_fmac_f32_e32 v122, v103, v107
	s_cselect_b64 vcc, -1, 0
	v_fmac_f32_e32 v123, v103, v108
	v_fmac_f32_e32 v121, v105, v107
	v_fmac_f32_e32 v120, v104, v107
	v_cndmask_b32_e32 v107, 0, v126, vcc
	v_fmac_f32_e32 v122, v104, v108
	v_fmac_f32_e32 v123, v104, v109
	s_mov_b32 s8, 16
	v_fmac_f32_e32 v120, v105, v108
	s_and_b64 vcc, exec, s[2:3]
	s_mov_b64 s[2:3], 0
	v_fmac_f32_e32 v122, v105, v109
	v_fmac_f32_e32 v123, v105, v107
	ds_write_b32 v129, v114
	ds_write_b32 v130, v115
	ds_write_b32 v131, v116
	ds_write_b32 v132, v117
	ds_write_b32 v133, v118
	ds_write_b32 v149, v119
	ds_write_b32 v150, v121
	ds_write_b32 v151, v120
	ds_write_b32 v152, v122
	ds_write_b32 v153, v123
	s_cbranch_vccnz .LBB0_102
	v_add_u32_e32 v0, s15, v89
	s_waitcnt lgkmcnt(0)
	s_barrier
	ds_read_b128 v[8:11], v0
	s_mov_b32 s2, 0x3727c5ac
	s_mov_b32 s4, 0x3727c5ac
	s_waitcnt lgkmcnt(0)
	v_mov_b32_e32 v0, v9
	v_mov_b32_e32 v1, v10
	v_mov_b32_e32 v2, v8
	v_mov_b32_e32 v3, v11
	v_pk_add_f32 v[0:1], v[0:1], v[2:3]
	s_nop 0
	v_add_f32_e32 v0, v0, v1
	s_waitcnt lgkmcnt(0)
	s_nop 1
	v_add_f32_dpp v35, v0, v0 quad_perm:[1,0,3,2] row_mask:0xf bank_mask:0xf
	global_load_dwordx4 v[0:3], v[82:83], off
	global_load_dwordx4 v[4:7], v[84:85], off
	s_waitcnt lgkmcnt(0)
	s_nop 1
	v_add_f32_dpp v35, v35, v35 quad_perm:[2,3,0,1] row_mask:0xf bank_mask:0xf
	s_waitcnt lgkmcnt(0)
	s_nop 1
	v_add_f32_dpp v35, v35, v35 row_half_mirror row_mask:0xf bank_mask:0xf
	s_waitcnt lgkmcnt(0)
	s_nop 1
	v_add_f32_dpp v35, v35, v35 row_mirror row_mask:0xf bank_mask:0xf
	ds_swizzle_b32 v86, v35 offset:swizzle(SWAP,16)
	s_waitcnt lgkmcnt(0)
	v_add_f32_e32 v35, v35, v86
	v_mov_b32_e32 v86, v35
	v_mov_b32_e32 v87, v35
	s_nop 1
	v_permlane32_swap_b32_e32 v86, v87
	v_add_u32_e32 v86, v86, v87
	v_sub_u32_e32 v86, v86, v35
	v_add_f32_e32 v35, v35, v86
	v_fmamk_f32 v9, v35, 0xbb800000, v9
	v_fmamk_f32 v8, v35, 0xbb800000, v8
	v_fmamk_f32 v11, v35, 0xbb800000, v11
	v_fmac_f32_e32 v10, 0xbb800000, v35
	v_pk_mul_f32 v[86:87], v[10:11], v[10:11]
	v_pk_mul_f32 v[90:91], v[8:9], v[8:9]
	s_nop 0
	v_pk_mov_b32 v[92:93], v[90:91], v[86:87] op_sel:[1,0]
	v_mov_b32_e32 v91, v87
	v_pk_add_f32 v[86:87], v[92:93], v[90:91]
	s_nop 0
	v_add_f32_e32 v35, v86, v87
	v_mov_b32_e32 v87, s2
	v_readlane_b32 s2, v253, 33
	s_add_u32 s2, s0, s2
	s_addc_u32 s3, s1, s56
	s_waitcnt lgkmcnt(0)
	s_nop 1
	v_add_f32_dpp v35, v35, v35 quad_perm:[1,0,3,2] row_mask:0xf bank_mask:0xf
	s_lshl_b64 s[2:3], s[2:3], 9
	s_waitcnt lgkmcnt(0)
	s_nop 1
	v_add_f32_dpp v35, v35, v35 quad_perm:[2,3,0,1] row_mask:0xf bank_mask:0xf
	s_waitcnt lgkmcnt(0)
; #define LAS __attribute__((address_space(3)))
; __device__ __forceinline__ unsigned cvt_pk_bf16(float lo, float hi) { unsigned r; asm volatile("v_cvt_pk_bf16_f32 %0, %1, %2" : "=v"(r) : "v"(lo), "v"(hi)); return r; }
; __device__ __forceinline__ float silu_f(float x) { return x * sigmoid_f(x); }
; __device__ __forceinline__ float ln_eps_s() { float e = LN_EPS; asm volatile("" : "+s"(e)); return e; }
; __device__ __forceinline__ void conv_item(int l, int it, LAS unsigned char* lds, const bf16_t* CGB, bf16_t* YC, const float* conv_w, const float* conv_b,
;                                           const float* conv_ln_g, const float* conv_ln_b, int tid, int lane, int wave) {
;     ...
;         for (int i = 0; i < 8; ++i) {
;             const int row = wave * 8 + i;
;             f32x4 v = *(const LAS f32x4*)(cv + row * BW + lane * 4);
;             const float mean = wave_sum((v.x + v.y) + (v.z + v.w)) * (1.f / BW);
;             v = v - mean;
;             const float rstd = __builtin_amdgcn_rsqf(wave_sum((v.x * v.x + v.y * v.y) + (v.z * v.z + v.w * v.w)) * (1.f / BW) + ln_eps_s());
;             const f32x4 y = v * rstd * gg + bb;
;             u32x2 w; w.x = cvt_pk_bf16(silu_f(y.x), silu_f(y.y)); w.y = cvt_pk_bf16(silu_f(y.z), silu_f(y.w));
;             *(u32x2*)(YC + (size_t)3 * MTOK * BW + (r0 + row) * BW + lane * 4) = w;
	s_nop 1
	v_add_f32_dpp v35, v35, v35 row_half_mirror row_mask:0xf bank_mask:0xf
	s_waitcnt lgkmcnt(0)
	s_nop 1
	v_add_f32_dpp v35, v35, v35 row_mirror row_mask:0xf bank_mask:0xf
	ds_swizzle_b32 v86, v35 offset:swizzle(SWAP,16)
	s_waitcnt lgkmcnt(0)
	v_add_f32_e32 v35, v35, v86
	v_mov_b32_e32 v86, v35
	v_mov_b32_e32 v90, v35
	s_nop 1
	v_permlane32_swap_b32_e32 v86, v90
	v_add_u32_e32 v86, v86, v90
	v_sub_u32_e32 v86, v86, v35
	v_add_f32_e32 v35, v35, v86
	v_fmac_f32_e32 v87, 0x3b800000, v35
	v_rsq_f32_e32 v86, v87
	v_add_u32_e32 v35, s58, v89
	v_pk_mul_f32 v[8:9], v[8:9], v[86:87] op_sel_hi:[1,0]
	v_pk_mul_f32 v[10:11], v[10:11], v[86:87] op_sel_hi:[1,0]
	s_waitcnt vmcnt(0)
	v_pk_fma_f32 v[8:9], v[0:1], v[8:9], v[4:5]
	v_pk_fma_f32 v[10:11], v[2:3], v[10:11], v[6:7]
	v_mul_f32_e32 v86, 0xbfb8aa3b, v8
	v_mul_f32_e32 v87, 0xbfb8aa3b, v9
	v_mul_f32_e32 v90, 0xbfb8aa3b, v10
	v_mul_f32_e32 v91, 0xbfb8aa3b, v11
	v_exp_f32_e32 v86, v86
	v_exp_f32_e32 v87, v87
	v_exp_f32_e32 v90, v90
	v_exp_f32_e32 v91, v91
	v_add_f32_e32 v86, 1.0, v86
	v_add_f32_e32 v87, 1.0, v87
	v_add_f32_e32 v90, 1.0, v90
	v_add_f32_e32 v91, 1.0, v91
	v_rcp_f32_e32 v86, v86
	v_rcp_f32_e32 v87, v87
	v_rcp_f32_e32 v90, v90
	v_rcp_f32_e32 v91, v91
	v_mul_f32_e32 v8, v8, v86
	v_mul_f32_e32 v9, v9, v87
	v_mul_f32_e32 v10, v10, v90
	v_mul_f32_e32 v11, v11, v91
	v_cvt_pk_bf16_f32 v86, v8, v9
	v_cvt_pk_bf16_f32 v87, v10, v11
	ds_read_b128 v[8:11], v35
	s_waitcnt lgkmcnt(0)
	v_mov_b32_e32 v90, v9
	v_mov_b32_e32 v91, v10
	v_mov_b32_e32 v92, v8
	v_mov_b32_e32 v93, v11
	v_pk_add_f32 v[90:91], v[90:91], v[92:93]
	s_nop 0
	v_add_f32_e32 v35, v90, v91
	s_waitcnt lgkmcnt(0)
	s_nop 1
	v_add_f32_dpp v35, v35, v35 quad_perm:[1,0,3,2] row_mask:0xf bank_mask:0xf
	s_waitcnt lgkmcnt(0)
	s_nop 1
	v_add_f32_dpp v35, v35, v35 quad_perm:[2,3,0,1] row_mask:0xf bank_mask:0xf
	s_waitcnt lgkmcnt(0)
	s_nop 1
	v_add_f32_dpp v35, v35, v35 row_half_mirror row_mask:0xf bank_mask:0xf
	s_waitcnt lgkmcnt(0)
	s_nop 1
	v_add_f32_dpp v35, v35, v35 row_mirror row_mask:0xf bank_mask:0xf
	ds_swizzle_b32 v90, v35 offset:swizzle(SWAP,16)
	s_waitcnt lgkmcnt(0)
	v_add_f32_e32 v35, v35, v90
	v_mov_b32_e32 v90, v35
	v_mov_b32_e32 v91, v35
	s_nop 1
	v_permlane32_swap_b32_e32 v90, v91
	v_add_u32_e32 v90, v90, v91
	v_sub_u32_e32 v90, v90, v35
	v_add_f32_e32 v35, v35, v90
	v_fmamk_f32 v9, v35, 0xbb800000, v9
	v_fmamk_f32 v8, v35, 0xbb800000, v8
	v_fmamk_f32 v11, v35, 0xbb800000, v11
	v_fmac_f32_e32 v10, 0xbb800000, v35
	v_pk_mul_f32 v[90:91], v[10:11], v[10:11]
	v_pk_mul_f32 v[92:93], v[8:9], v[8:9]
	s_nop 0
	v_pk_mov_b32 v[94:95], v[92:93], v[90:91] op_sel:[1,0]
	v_mov_b32_e32 v93, v91
	v_pk_add_f32 v[90:91], v[94:95], v[92:93]
	s_nop 0
	v_add_f32_e32 v35, v90, v91
	s_waitcnt lgkmcnt(0)
	s_nop 1
	v_add_f32_dpp v35, v35, v35 quad_perm:[1,0,3,2] row_mask:0xf bank_mask:0xf
	s_waitcnt lgkmcnt(0)
	s_nop 1
	v_add_f32_dpp v35, v35, v35 quad_perm:[2,3,0,1] row_mask:0xf bank_mask:0xf
	s_waitcnt lgkmcnt(0)
	s_nop 1
	v_add_f32_dpp v35, v35, v35 row_half_mirror row_mask:0xf bank_mask:0xf
	s_waitcnt lgkmcnt(0)
	s_nop 1
	v_add_f32_dpp v35, v35, v35 row_mirror row_mask:0xf bank_mask:0xf
	ds_swizzle_b32 v92, v35 offset:swizzle(SWAP,16)
	v_lshl_add_u64 v[90:91], v[12:13], 0, s[2:3]
	global_store_dwordx2 v[90:91], v[86:87], off
	s_add_u32 s2, s0, s57
	s_waitcnt lgkmcnt(0)
	v_add_f32_e32 v35, v35, v92
	v_mov_b32_e32 v87, v35
	v_mov_b32_e32 v90, v35
	s_nop 1
	v_permlane32_swap_b32_e32 v87, v90
	v_add_u32_e32 v87, v87, v90
	v_sub_u32_e32 v87, v87, v35
	v_mov_b32_e32 v86, s4
	v_add_f32_e32 v35, v35, v87
	v_fmac_f32_e32 v86, 0x3b800000, v35
	v_rsq_f32_e32 v86, v86
	v_add_u32_e32 v35, s61, v89
	s_addc_u32 s3, s1, s59
	s_lshl_b64 s[2:3], s[2:3], 9
	v_pk_mul_f32 v[8:9], v[8:9], v[86:87] op_sel_hi:[1,0]
	v_pk_mul_f32 v[10:11], v[10:11], v[86:87] op_sel_hi:[1,0]
	v_pk_fma_f32 v[8:9], v[0:1], v[8:9], v[4:5]
	v_pk_fma_f32 v[10:11], v[2:3], v[10:11], v[6:7]
	v_mul_f32_e32 v86, 0xbfb8aa3b, v8
	v_mul_f32_e32 v87, 0xbfb8aa3b, v9
	v_mul_f32_e32 v90, 0xbfb8aa3b, v10
	v_mul_f32_e32 v91, 0xbfb8aa3b, v11
	v_exp_f32_e32 v86, v86
	v_exp_f32_e32 v87, v87
	v_exp_f32_e32 v90, v90
	v_exp_f32_e32 v91, v91
	v_add_f32_e32 v86, 1.0, v86
	v_add_f32_e32 v87, 1.0, v87
	v_add_f32_e32 v90, 1.0, v90
	v_add_f32_e32 v91, 1.0, v91
	v_rcp_f32_e32 v86, v86
	v_rcp_f32_e32 v87, v87
	v_rcp_f32_e32 v90, v90
	v_rcp_f32_e32 v91, v91
	v_mul_f32_e32 v8, v8, v86
	v_mul_f32_e32 v9, v9, v87
	v_mul_f32_e32 v10, v10, v90
	v_mul_f32_e32 v11, v11, v91
	v_cvt_pk_bf16_f32 v86, v8, v9
	v_cvt_pk_bf16_f32 v87, v10, v11
	ds_read_b128 v[8:11], v35
	s_mov_b32 s4, 0x3727c5ac
	s_waitcnt lgkmcnt(0)
	v_mov_b32_e32 v90, v9
	v_mov_b32_e32 v91, v10
	v_mov_b32_e32 v92, v8
	v_mov_b32_e32 v93, v11
	v_pk_add_f32 v[90:91], v[90:91], v[92:93]
	s_nop 0
	v_add_f32_e32 v35, v90, v91
	s_waitcnt lgkmcnt(0)
	s_nop 1
	v_add_f32_dpp v35, v35, v35 quad_perm:[1,0,3,2] row_mask:0xf bank_mask:0xf
	s_waitcnt lgkmcnt(0)
	s_nop 1
	v_add_f32_dpp v35, v35, v35 quad_perm:[2,3,0,1] row_mask:0xf bank_mask:0xf
	s_waitcnt lgkmcnt(0)
	s_nop 1
	v_add_f32_dpp v35, v35, v35 row_half_mirror row_mask:0xf bank_mask:0xf
	s_waitcnt lgkmcnt(0)
	s_nop 1
	v_add_f32_dpp v35, v35, v35 row_mirror row_mask:0xf bank_mask:0xf
	ds_swizzle_b32 v90, v35 offset:swizzle(SWAP,16)
	s_waitcnt lgkmcnt(0)
	v_add_f32_e32 v35, v35, v90
	v_mov_b32_e32 v90, v35
	v_mov_b32_e32 v91, v35
	s_nop 1
	v_permlane32_swap_b32_e32 v90, v91
	v_add_u32_e32 v90, v90, v91
	v_sub_u32_e32 v90, v90, v35
	v_add_f32_e32 v35, v35, v90
	v_fmamk_f32 v9, v35, 0xbb800000, v9
	v_fmamk_f32 v8, v35, 0xbb800000, v8
	v_fmamk_f32 v11, v35, 0xbb800000, v11
	v_fmac_f32_e32 v10, 0xbb800000, v35
	v_pk_mul_f32 v[90:91], v[10:11], v[10:11]
	v_pk_mul_f32 v[92:93], v[8:9], v[8:9]
	s_nop 0
	v_pk_mov_b32 v[94:95], v[92:93], v[90:91] op_sel:[1,0]
	v_mov_b32_e32 v93, v91
	v_pk_add_f32 v[90:91], v[94:95], v[92:93]
	s_nop 0
	v_add_f32_e32 v35, v90, v91
	s_waitcnt lgkmcnt(0)
; #define LAS __attribute__((address_space(3)))
; __device__ __forceinline__ unsigned cvt_pk_bf16(float lo, float hi) { unsigned r; asm volatile("v_cvt_pk_bf16_f32 %0, %1, %2" : "=v"(r) : "v"(lo), "v"(hi)); return r; }
; __device__ __forceinline__ float silu_f(float x) { return x * sigmoid_f(x); }
; __device__ __forceinline__ float ln_eps_s() { float e = LN_EPS; asm volatile("" : "+s"(e)); return e; }
; __device__ __forceinline__ void conv_item(int l, int it, LAS unsigned char* lds, const bf16_t* CGB, bf16_t* YC, const float* conv_w, const float* conv_b,
;                                           const float* conv_ln_g, const float* conv_ln_b, int tid, int lane, int wave) {
;     ...
;         for (int i = 0; i < 8; ++i) {
;             const int row = wave * 8 + i;
;             f32x4 v = *(const LAS f32x4*)(cv + row * BW + lane * 4);
;             const float mean = wave_sum((v.x + v.y) + (v.z + v.w)) * (1.f / BW);
;             v = v - mean;
;             const float rstd = __builtin_amdgcn_rsqf(wave_sum((v.x * v.x + v.y * v.y) + (v.z * v.z + v.w * v.w)) * (1.f / BW) + ln_eps_s());
;             const f32x4 y = v * rstd * gg + bb;
;             u32x2 w; w.x = cvt_pk_bf16(silu_f(y.x), silu_f(y.y)); w.y = cvt_pk_bf16(silu_f(y.z), silu_f(y.w));
;             *(u32x2*)(YC + (size_t)3 * MTOK * BW + (r0 + row) * BW + lane * 4) = w;
	s_nop 1
	v_add_f32_dpp v35, v35, v35 quad_perm:[1,0,3,2] row_mask:0xf bank_mask:0xf
	s_waitcnt lgkmcnt(0)
	s_nop 1
	v_add_f32_dpp v35, v35, v35 quad_perm:[2,3,0,1] row_mask:0xf bank_mask:0xf
	s_waitcnt lgkmcnt(0)
	s_nop 1
	v_add_f32_dpp v35, v35, v35 row_half_mirror row_mask:0xf bank_mask:0xf
	s_waitcnt lgkmcnt(0)
	s_nop 1
	v_add_f32_dpp v35, v35, v35 row_mirror row_mask:0xf bank_mask:0xf
	ds_swizzle_b32 v92, v35 offset:swizzle(SWAP,16)
	v_lshl_add_u64 v[90:91], v[12:13], 0, s[2:3]
	global_store_dwordx2 v[90:91], v[86:87], off
	s_add_u32 s2, s0, s60
	s_waitcnt lgkmcnt(0)
	v_add_f32_e32 v35, v35, v92
	v_mov_b32_e32 v87, v35
	v_mov_b32_e32 v90, v35
	s_nop 1
	v_permlane32_swap_b32_e32 v87, v90
	v_add_u32_e32 v87, v87, v90
	v_sub_u32_e32 v87, v87, v35
	v_mov_b32_e32 v86, s4
	v_add_f32_e32 v35, v35, v87
	v_fmac_f32_e32 v86, 0x3b800000, v35
	v_rsq_f32_e32 v86, v86
	v_add_u32_e32 v35, s64, v89
	s_addc_u32 s3, s1, s62
	s_lshl_b64 s[2:3], s[2:3], 9
	v_pk_mul_f32 v[8:9], v[8:9], v[86:87] op_sel_hi:[1,0]
	v_pk_mul_f32 v[10:11], v[10:11], v[86:87] op_sel_hi:[1,0]
	v_pk_fma_f32 v[8:9], v[0:1], v[8:9], v[4:5]
	v_pk_fma_f32 v[10:11], v[2:3], v[10:11], v[6:7]
	v_mul_f32_e32 v86, 0xbfb8aa3b, v8
	v_mul_f32_e32 v87, 0xbfb8aa3b, v9
	v_mul_f32_e32 v90, 0xbfb8aa3b, v10
	v_mul_f32_e32 v91, 0xbfb8aa3b, v11
	v_exp_f32_e32 v86, v86
	v_exp_f32_e32 v87, v87
	v_exp_f32_e32 v90, v90
	v_exp_f32_e32 v91, v91
	v_add_f32_e32 v86, 1.0, v86
	v_add_f32_e32 v87, 1.0, v87
	v_add_f32_e32 v90, 1.0, v90
	v_add_f32_e32 v91, 1.0, v91
	v_rcp_f32_e32 v86, v86
	v_rcp_f32_e32 v87, v87
	v_rcp_f32_e32 v90, v90
	v_rcp_f32_e32 v91, v91
	v_mul_f32_e32 v8, v8, v86
	v_mul_f32_e32 v9, v9, v87
	v_mul_f32_e32 v10, v10, v90
	v_mul_f32_e32 v11, v11, v91
	v_cvt_pk_bf16_f32 v86, v8, v9
	v_cvt_pk_bf16_f32 v87, v10, v11
	ds_read_b128 v[8:11], v35
	s_mov_b32 s4, 0x3727c5ac
	s_waitcnt lgkmcnt(0)
	v_mov_b32_e32 v90, v9
	v_mov_b32_e32 v91, v10
	v_mov_b32_e32 v92, v8
	v_mov_b32_e32 v93, v11
	v_pk_add_f32 v[90:91], v[90:91], v[92:93]
	s_nop 0
	v_add_f32_e32 v35, v90, v91
	s_waitcnt lgkmcnt(0)
	s_nop 1
	v_add_f32_dpp v35, v35, v35 quad_perm:[1,0,3,2] row_mask:0xf bank_mask:0xf
	s_waitcnt lgkmcnt(0)
	s_nop 1
	v_add_f32_dpp v35, v35, v35 quad_perm:[2,3,0,1] row_mask:0xf bank_mask:0xf
	s_waitcnt lgkmcnt(0)
	s_nop 1
	v_add_f32_dpp v35, v35, v35 row_half_mirror row_mask:0xf bank_mask:0xf
	s_waitcnt lgkmcnt(0)
	s_nop 1
	v_add_f32_dpp v35, v35, v35 row_mirror row_mask:0xf bank_mask:0xf
	ds_swizzle_b32 v90, v35 offset:swizzle(SWAP,16)
	s_waitcnt lgkmcnt(0)
	v_add_f32_e32 v35, v35, v90
	v_mov_b32_e32 v90, v35
	v_mov_b32_e32 v91, v35
	s_nop 1
	v_permlane32_swap_b32_e32 v90, v91
	v_add_u32_e32 v90, v90, v91
	v_sub_u32_e32 v90, v90, v35
	v_add_f32_e32 v35, v35, v90
	v_fmamk_f32 v9, v35, 0xbb800000, v9
	v_fmamk_f32 v8, v35, 0xbb800000, v8
	v_fmamk_f32 v11, v35, 0xbb800000, v11
	v_fmac_f32_e32 v10, 0xbb800000, v35
	v_pk_mul_f32 v[90:91], v[10:11], v[10:11]
	v_pk_mul_f32 v[92:93], v[8:9], v[8:9]
	s_nop 0
	v_pk_mov_b32 v[94:95], v[92:93], v[90:91] op_sel:[1,0]
	v_mov_b32_e32 v93, v91
	v_pk_add_f32 v[90:91], v[94:95], v[92:93]
	s_nop 0
	v_add_f32_e32 v35, v90, v91
	s_waitcnt lgkmcnt(0)
	s_nop 1
	v_add_f32_dpp v35, v35, v35 quad_perm:[1,0,3,2] row_mask:0xf bank_mask:0xf
	s_waitcnt lgkmcnt(0)
	s_nop 1
	v_add_f32_dpp v35, v35, v35 quad_perm:[2,3,0,1] row_mask:0xf bank_mask:0xf
	s_waitcnt lgkmcnt(0)
	s_nop 1
	v_add_f32_dpp v35, v35, v35 row_half_mirror row_mask:0xf bank_mask:0xf
	s_waitcnt lgkmcnt(0)
	s_nop 1
	v_add_f32_dpp v35, v35, v35 row_mirror row_mask:0xf bank_mask:0xf
	ds_swizzle_b32 v92, v35 offset:swizzle(SWAP,16)
	v_lshl_add_u64 v[90:91], v[12:13], 0, s[2:3]
	global_store_dwordx2 v[90:91], v[86:87], off
	s_add_u32 s2, s0, s63
	s_waitcnt lgkmcnt(0)
	v_add_f32_e32 v35, v35, v92
	v_mov_b32_e32 v87, v35
	v_mov_b32_e32 v90, v35
	s_nop 1
	v_permlane32_swap_b32_e32 v87, v90
	v_add_u32_e32 v87, v87, v90
	v_sub_u32_e32 v87, v87, v35
	v_mov_b32_e32 v86, s4
	v_add_f32_e32 v35, v35, v87
	v_fmac_f32_e32 v86, 0x3b800000, v35
	v_rsq_f32_e32 v86, v86
	v_add_u32_e32 v35, s67, v89
	s_addc_u32 s3, s1, s65
	s_lshl_b64 s[2:3], s[2:3], 9
	v_pk_mul_f32 v[8:9], v[8:9], v[86:87] op_sel_hi:[1,0]
	v_pk_mul_f32 v[10:11], v[10:11], v[86:87] op_sel_hi:[1,0]
	v_pk_fma_f32 v[8:9], v[0:1], v[8:9], v[4:5]
	v_pk_fma_f32 v[10:11], v[2:3], v[10:11], v[6:7]
	v_mul_f32_e32 v86, 0xbfb8aa3b, v8
	v_mul_f32_e32 v87, 0xbfb8aa3b, v9
	v_mul_f32_e32 v90, 0xbfb8aa3b, v10
	v_mul_f32_e32 v91, 0xbfb8aa3b, v11
	v_exp_f32_e32 v86, v86
	v_exp_f32_e32 v87, v87
	v_exp_f32_e32 v90, v90
	v_exp_f32_e32 v91, v91
	v_add_f32_e32 v86, 1.0, v86
	v_add_f32_e32 v87, 1.0, v87
	v_add_f32_e32 v90, 1.0, v90
	v_add_f32_e32 v91, 1.0, v91
	v_rcp_f32_e32 v86, v86
	v_rcp_f32_e32 v87, v87
	v_rcp_f32_e32 v90, v90
	v_rcp_f32_e32 v91, v91
	v_mul_f32_e32 v8, v8, v86
	v_mul_f32_e32 v9, v9, v87
	v_mul_f32_e32 v10, v10, v90
	v_mul_f32_e32 v11, v11, v91
	v_cvt_pk_bf16_f32 v86, v8, v9
	v_cvt_pk_bf16_f32 v87, v10, v11
	ds_read_b128 v[8:11], v35
	s_mov_b32 s4, 0x3727c5ac
	s_waitcnt lgkmcnt(0)
	v_mov_b32_e32 v90, v9
	v_mov_b32_e32 v91, v10
	v_mov_b32_e32 v92, v8
	v_mov_b32_e32 v93, v11
	v_pk_add_f32 v[90:91], v[90:91], v[92:93]
	s_nop 0
	v_add_f32_e32 v35, v90, v91
	s_waitcnt lgkmcnt(0)
	s_nop 1
	v_add_f32_dpp v35, v35, v35 quad_perm:[1,0,3,2] row_mask:0xf bank_mask:0xf
	s_waitcnt lgkmcnt(0)
	s_nop 1
	v_add_f32_dpp v35, v35, v35 quad_perm:[2,3,0,1] row_mask:0xf bank_mask:0xf
	s_waitcnt lgkmcnt(0)
	s_nop 1
	v_add_f32_dpp v35, v35, v35 row_half_mirror row_mask:0xf bank_mask:0xf
	s_waitcnt lgkmcnt(0)
	s_nop 1
	v_add_f32_dpp v35, v35, v35 row_mirror row_mask:0xf bank_mask:0xf
	ds_swizzle_b32 v90, v35 offset:swizzle(SWAP,16)
	s_waitcnt lgkmcnt(0)
; #define LAS __attribute__((address_space(3)))
; __device__ __forceinline__ unsigned cvt_pk_bf16(float lo, float hi) { unsigned r; asm volatile("v_cvt_pk_bf16_f32 %0, %1, %2" : "=v"(r) : "v"(lo), "v"(hi)); return r; }
; __device__ __forceinline__ float silu_f(float x) { return x * sigmoid_f(x); }
; __device__ __forceinline__ float ln_eps_s() { float e = LN_EPS; asm volatile("" : "+s"(e)); return e; }
; __device__ __forceinline__ void conv_item(int l, int it, LAS unsigned char* lds, const bf16_t* CGB, bf16_t* YC, const float* conv_w, const float* conv_b,
;                                           const float* conv_ln_g, const float* conv_ln_b, int tid, int lane, int wave) {
;     ...
;         for (int i = 0; i < 8; ++i) {
;             const int row = wave * 8 + i;
;             f32x4 v = *(const LAS f32x4*)(cv + row * BW + lane * 4);
;             const float mean = wave_sum((v.x + v.y) + (v.z + v.w)) * (1.f / BW);
;             v = v - mean;
;             const float rstd = __builtin_amdgcn_rsqf(wave_sum((v.x * v.x + v.y * v.y) + (v.z * v.z + v.w * v.w)) * (1.f / BW) + ln_eps_s());
;             const f32x4 y = v * rstd * gg + bb;
;             u32x2 w; w.x = cvt_pk_bf16(silu_f(y.x), silu_f(y.y)); w.y = cvt_pk_bf16(silu_f(y.z), silu_f(y.w));
;             *(u32x2*)(YC + (size_t)3 * MTOK * BW + (r0 + row) * BW + lane * 4) = w;
	v_add_f32_e32 v35, v35, v90
	v_mov_b32_e32 v90, v35
	v_mov_b32_e32 v91, v35
	s_nop 1
	v_permlane32_swap_b32_e32 v90, v91
	v_add_u32_e32 v90, v90, v91
	v_sub_u32_e32 v90, v90, v35
	v_add_f32_e32 v35, v35, v90
	v_fmamk_f32 v9, v35, 0xbb800000, v9
	v_fmamk_f32 v8, v35, 0xbb800000, v8
	v_fmamk_f32 v11, v35, 0xbb800000, v11
	v_fmac_f32_e32 v10, 0xbb800000, v35
	v_pk_mul_f32 v[90:91], v[10:11], v[10:11]
	v_pk_mul_f32 v[92:93], v[8:9], v[8:9]
	s_nop 0
	v_pk_mov_b32 v[94:95], v[92:93], v[90:91] op_sel:[1,0]
	v_mov_b32_e32 v93, v91
	v_pk_add_f32 v[90:91], v[94:95], v[92:93]
	s_nop 0
	v_add_f32_e32 v35, v90, v91
	s_waitcnt lgkmcnt(0)
	s_nop 1
	v_add_f32_dpp v35, v35, v35 quad_perm:[1,0,3,2] row_mask:0xf bank_mask:0xf
	s_waitcnt lgkmcnt(0)
	s_nop 1
	v_add_f32_dpp v35, v35, v35 quad_perm:[2,3,0,1] row_mask:0xf bank_mask:0xf
	s_waitcnt lgkmcnt(0)
	s_nop 1
	v_add_f32_dpp v35, v35, v35 row_half_mirror row_mask:0xf bank_mask:0xf
	s_waitcnt lgkmcnt(0)
	s_nop 1
	v_add_f32_dpp v35, v35, v35 row_mirror row_mask:0xf bank_mask:0xf
	ds_swizzle_b32 v92, v35 offset:swizzle(SWAP,16)
	v_lshl_add_u64 v[90:91], v[12:13], 0, s[2:3]
	global_store_dwordx2 v[90:91], v[86:87], off
	s_add_u32 s2, s0, s66
	s_waitcnt lgkmcnt(0)
	v_add_f32_e32 v35, v35, v92
	v_mov_b32_e32 v87, v35
	v_mov_b32_e32 v90, v35
	s_nop 1
	v_permlane32_swap_b32_e32 v87, v90
	v_add_u32_e32 v87, v87, v90
	v_sub_u32_e32 v87, v87, v35
	v_mov_b32_e32 v86, s4
	v_add_f32_e32 v35, v35, v87
	v_fmac_f32_e32 v86, 0x3b800000, v35
	v_rsq_f32_e32 v86, v86
	v_add_u32_e32 v35, s70, v89
	s_addc_u32 s3, s1, s68
	s_lshl_b64 s[2:3], s[2:3], 9
	v_pk_mul_f32 v[8:9], v[8:9], v[86:87] op_sel_hi:[1,0]
	v_pk_mul_f32 v[10:11], v[10:11], v[86:87] op_sel_hi:[1,0]
	v_pk_fma_f32 v[8:9], v[0:1], v[8:9], v[4:5]
	v_pk_fma_f32 v[10:11], v[2:3], v[10:11], v[6:7]
	v_mul_f32_e32 v86, 0xbfb8aa3b, v8
	v_mul_f32_e32 v87, 0xbfb8aa3b, v9
	v_mul_f32_e32 v90, 0xbfb8aa3b, v10
	v_mul_f32_e32 v91, 0xbfb8aa3b, v11
	v_exp_f32_e32 v86, v86
	v_exp_f32_e32 v87, v87
	v_exp_f32_e32 v90, v90
	v_exp_f32_e32 v91, v91
	v_add_f32_e32 v86, 1.0, v86
	v_add_f32_e32 v87, 1.0, v87
	v_add_f32_e32 v90, 1.0, v90
	v_add_f32_e32 v91, 1.0, v91
	v_rcp_f32_e32 v86, v86
	v_rcp_f32_e32 v87, v87
	v_rcp_f32_e32 v90, v90
	v_rcp_f32_e32 v91, v91
	v_mul_f32_e32 v8, v8, v86
	v_mul_f32_e32 v9, v9, v87
	v_mul_f32_e32 v10, v10, v90
	v_mul_f32_e32 v11, v11, v91
	v_cvt_pk_bf16_f32 v86, v8, v9
	v_cvt_pk_bf16_f32 v87, v10, v11
	ds_read_b128 v[8:11], v35
	s_mov_b32 s4, 0x3727c5ac
	s_waitcnt lgkmcnt(0)
	v_mov_b32_e32 v90, v9
	v_mov_b32_e32 v91, v10
	v_mov_b32_e32 v92, v8
	v_mov_b32_e32 v93, v11
	v_pk_add_f32 v[90:91], v[90:91], v[92:93]
	s_nop 0
	v_add_f32_e32 v35, v90, v91
	s_waitcnt lgkmcnt(0)
	s_nop 1
	v_add_f32_dpp v35, v35, v35 quad_perm:[1,0,3,2] row_mask:0xf bank_mask:0xf
	s_waitcnt lgkmcnt(0)
	s_nop 1
	v_add_f32_dpp v35, v35, v35 quad_perm:[2,3,0,1] row_mask:0xf bank_mask:0xf
	s_waitcnt lgkmcnt(0)
	s_nop 1
	v_add_f32_dpp v35, v35, v35 row_half_mirror row_mask:0xf bank_mask:0xf
	s_waitcnt lgkmcnt(0)
	s_nop 1
	v_add_f32_dpp v35, v35, v35 row_mirror row_mask:0xf bank_mask:0xf
	ds_swizzle_b32 v90, v35 offset:swizzle(SWAP,16)
	s_waitcnt lgkmcnt(0)
	v_add_f32_e32 v35, v35, v90
	v_mov_b32_e32 v90, v35
	v_mov_b32_e32 v91, v35
	s_nop 1
	v_permlane32_swap_b32_e32 v90, v91
	v_add_u32_e32 v90, v90, v91
	v_sub_u32_e32 v90, v90, v35
	v_add_f32_e32 v35, v35, v90
	v_fmamk_f32 v9, v35, 0xbb800000, v9
	v_fmamk_f32 v8, v35, 0xbb800000, v8
	v_fmamk_f32 v11, v35, 0xbb800000, v11
	v_fmac_f32_e32 v10, 0xbb800000, v35
	v_pk_mul_f32 v[90:91], v[10:11], v[10:11]
	v_pk_mul_f32 v[92:93], v[8:9], v[8:9]
	s_nop 0
	v_pk_mov_b32 v[94:95], v[92:93], v[90:91] op_sel:[1,0]
	v_mov_b32_e32 v93, v91
	v_pk_add_f32 v[90:91], v[94:95], v[92:93]
	s_nop 0
	v_add_f32_e32 v35, v90, v91
	s_waitcnt lgkmcnt(0)
	s_nop 1
	v_add_f32_dpp v35, v35, v35 quad_perm:[1,0,3,2] row_mask:0xf bank_mask:0xf
	s_waitcnt lgkmcnt(0)
	s_nop 1
	v_add_f32_dpp v35, v35, v35 quad_perm:[2,3,0,1] row_mask:0xf bank_mask:0xf
	s_waitcnt lgkmcnt(0)
	s_nop 1
	v_add_f32_dpp v35, v35, v35 row_half_mirror row_mask:0xf bank_mask:0xf
	s_waitcnt lgkmcnt(0)
	s_nop 1
	v_add_f32_dpp v35, v35, v35 row_mirror row_mask:0xf bank_mask:0xf
	ds_swizzle_b32 v92, v35 offset:swizzle(SWAP,16)
	v_lshl_add_u64 v[90:91], v[12:13], 0, s[2:3]
	global_store_dwordx2 v[90:91], v[86:87], off
	s_add_u32 s2, s0, s69
	s_waitcnt lgkmcnt(0)
	v_add_f32_e32 v35, v35, v92
	v_mov_b32_e32 v87, v35
	v_mov_b32_e32 v90, v35
	s_nop 1
	v_permlane32_swap_b32_e32 v87, v90
	v_add_u32_e32 v87, v87, v90
	v_sub_u32_e32 v87, v87, v35
	v_mov_b32_e32 v86, s4
	v_add_f32_e32 v35, v35, v87
	v_fmac_f32_e32 v86, 0x3b800000, v35
	v_rsq_f32_e32 v86, v86
	v_add_u32_e32 v35, s73, v89
	s_addc_u32 s3, s1, s71
	s_lshl_b64 s[2:3], s[2:3], 9
	v_pk_mul_f32 v[8:9], v[8:9], v[86:87] op_sel_hi:[1,0]
	v_pk_mul_f32 v[10:11], v[10:11], v[86:87] op_sel_hi:[1,0]
	v_pk_fma_f32 v[8:9], v[0:1], v[8:9], v[4:5]
	v_pk_fma_f32 v[10:11], v[2:3], v[10:11], v[6:7]
	v_mul_f32_e32 v86, 0xbfb8aa3b, v8
	v_mul_f32_e32 v87, 0xbfb8aa3b, v9
	v_mul_f32_e32 v90, 0xbfb8aa3b, v10
	v_mul_f32_e32 v91, 0xbfb8aa3b, v11
	v_exp_f32_e32 v86, v86
	v_exp_f32_e32 v87, v87
	v_exp_f32_e32 v90, v90
	v_exp_f32_e32 v91, v91
	v_add_f32_e32 v86, 1.0, v86
	v_add_f32_e32 v87, 1.0, v87
	v_add_f32_e32 v90, 1.0, v90
	v_add_f32_e32 v91, 1.0, v91
	v_rcp_f32_e32 v86, v86
	v_rcp_f32_e32 v87, v87
	v_rcp_f32_e32 v90, v90
	v_rcp_f32_e32 v91, v91
	v_mul_f32_e32 v8, v8, v86
	v_mul_f32_e32 v9, v9, v87
	v_mul_f32_e32 v10, v10, v90
	v_mul_f32_e32 v11, v11, v91
	v_cvt_pk_bf16_f32 v86, v8, v9
	v_cvt_pk_bf16_f32 v87, v10, v11
	ds_read_b128 v[8:11], v35
	s_mov_b32 s4, 0x3727c5ac
	s_waitcnt lgkmcnt(0)
; #define LAS __attribute__((address_space(3)))
; __device__ __forceinline__ unsigned cvt_pk_bf16(float lo, float hi) { unsigned r; asm volatile("v_cvt_pk_bf16_f32 %0, %1, %2" : "=v"(r) : "v"(lo), "v"(hi)); return r; }
; __device__ __forceinline__ float silu_f(float x) { return x * sigmoid_f(x); }
; __device__ __forceinline__ float ln_eps_s() { float e = LN_EPS; asm volatile("" : "+s"(e)); return e; }
; __device__ __forceinline__ void conv_item(int l, int it, LAS unsigned char* lds, const bf16_t* CGB, bf16_t* YC, const float* conv_w, const float* conv_b,
;                                           const float* conv_ln_g, const float* conv_ln_b, int tid, int lane, int wave) {
;     ...
;     const size_t r0 = (size_t)it * 64; const int pos0 = (int)(r0 & (SEQ - 1));
;     ...
;         for (int i = 0; i < 8; ++i) {
;             const int row = wave * 8 + i;
;             f32x4 v = *(const LAS f32x4*)(cv + row * BW + lane * 4);
;             const float mean = wave_sum((v.x + v.y) + (v.z + v.w)) * (1.f / BW);
;             v = v - mean;
;             const float rstd = __builtin_amdgcn_rsqf(wave_sum((v.x * v.x + v.y * v.y) + (v.z * v.z + v.w * v.w)) * (1.f / BW) + ln_eps_s());
;             const f32x4 y = v * rstd * gg + bb;
;             u32x2 w; w.x = cvt_pk_bf16(silu_f(y.x), silu_f(y.y)); w.y = cvt_pk_bf16(silu_f(y.z), silu_f(y.w));
;             *(u32x2*)(YC + (size_t)3 * MTOK * BW + (r0 + row) * BW + lane * 4) = w;
;         }
;     }
;     __syncthreads();
	v_mov_b32_e32 v90, v9
	v_mov_b32_e32 v91, v10
	v_mov_b32_e32 v92, v8
	v_mov_b32_e32 v93, v11
	v_pk_add_f32 v[90:91], v[90:91], v[92:93]
	s_nop 0
	v_add_f32_e32 v35, v90, v91
	s_waitcnt lgkmcnt(0)
	s_nop 1
	v_add_f32_dpp v35, v35, v35 quad_perm:[1,0,3,2] row_mask:0xf bank_mask:0xf
	s_waitcnt lgkmcnt(0)
	s_nop 1
	v_add_f32_dpp v35, v35, v35 quad_perm:[2,3,0,1] row_mask:0xf bank_mask:0xf
	s_waitcnt lgkmcnt(0)
	s_nop 1
	v_add_f32_dpp v35, v35, v35 row_half_mirror row_mask:0xf bank_mask:0xf
	s_waitcnt lgkmcnt(0)
	s_nop 1
	v_add_f32_dpp v35, v35, v35 row_mirror row_mask:0xf bank_mask:0xf
	ds_swizzle_b32 v90, v35 offset:swizzle(SWAP,16)
	s_waitcnt lgkmcnt(0)
	v_add_f32_e32 v35, v35, v90
	v_mov_b32_e32 v90, v35
	v_mov_b32_e32 v91, v35
	s_nop 1
	v_permlane32_swap_b32_e32 v90, v91
	v_add_u32_e32 v90, v90, v91
	v_sub_u32_e32 v90, v90, v35
	v_add_f32_e32 v35, v35, v90
	v_fmamk_f32 v9, v35, 0xbb800000, v9
	v_fmamk_f32 v8, v35, 0xbb800000, v8
	v_fmamk_f32 v11, v35, 0xbb800000, v11
	v_fmac_f32_e32 v10, 0xbb800000, v35
	v_pk_mul_f32 v[90:91], v[10:11], v[10:11]
	v_pk_mul_f32 v[92:93], v[8:9], v[8:9]
	s_nop 0
	v_pk_mov_b32 v[94:95], v[92:93], v[90:91] op_sel:[1,0]
	v_mov_b32_e32 v93, v91
	v_pk_add_f32 v[90:91], v[94:95], v[92:93]
	s_nop 0
	v_add_f32_e32 v35, v90, v91
	s_waitcnt lgkmcnt(0)
	s_nop 1
	v_add_f32_dpp v35, v35, v35 quad_perm:[1,0,3,2] row_mask:0xf bank_mask:0xf
	s_waitcnt lgkmcnt(0)
	s_nop 1
	v_add_f32_dpp v35, v35, v35 quad_perm:[2,3,0,1] row_mask:0xf bank_mask:0xf
	s_waitcnt lgkmcnt(0)
	s_nop 1
	v_add_f32_dpp v35, v35, v35 row_half_mirror row_mask:0xf bank_mask:0xf
	s_waitcnt lgkmcnt(0)
	s_nop 1
	v_add_f32_dpp v35, v35, v35 row_mirror row_mask:0xf bank_mask:0xf
	ds_swizzle_b32 v92, v35 offset:swizzle(SWAP,16)
	v_lshl_add_u64 v[90:91], v[12:13], 0, s[2:3]
	global_store_dwordx2 v[90:91], v[86:87], off
	s_add_u32 s2, s0, s72
	s_waitcnt lgkmcnt(0)
	v_add_f32_e32 v35, v35, v92
	v_mov_b32_e32 v87, v35
	v_mov_b32_e32 v90, v35
	s_nop 1
	v_permlane32_swap_b32_e32 v87, v90
	v_add_u32_e32 v87, v87, v90
	v_sub_u32_e32 v87, v87, v35
	v_mov_b32_e32 v86, s4
	v_add_f32_e32 v35, v35, v87
	v_fmac_f32_e32 v86, 0x3b800000, v35
	v_rsq_f32_e32 v86, v86
	v_add_u32_e32 v35, s76, v89
	s_addc_u32 s3, s1, s74
	s_lshl_b64 s[2:3], s[2:3], 9
	v_pk_mul_f32 v[8:9], v[8:9], v[86:87] op_sel_hi:[1,0]
	v_pk_mul_f32 v[10:11], v[10:11], v[86:87] op_sel_hi:[1,0]
	v_pk_fma_f32 v[8:9], v[0:1], v[8:9], v[4:5]
	v_pk_fma_f32 v[10:11], v[2:3], v[10:11], v[6:7]
	v_mul_f32_e32 v86, 0xbfb8aa3b, v8
	v_mul_f32_e32 v87, 0xbfb8aa3b, v9
	v_mul_f32_e32 v90, 0xbfb8aa3b, v10
	v_mul_f32_e32 v91, 0xbfb8aa3b, v11
	v_exp_f32_e32 v86, v86
	v_exp_f32_e32 v87, v87
	v_exp_f32_e32 v90, v90
	v_exp_f32_e32 v91, v91
	v_add_f32_e32 v86, 1.0, v86
	v_add_f32_e32 v87, 1.0, v87
	v_add_f32_e32 v90, 1.0, v90
	v_add_f32_e32 v91, 1.0, v91
	v_rcp_f32_e32 v86, v86
	v_rcp_f32_e32 v87, v87
	v_rcp_f32_e32 v90, v90
	v_rcp_f32_e32 v91, v91
	v_mul_f32_e32 v8, v8, v86
	v_mul_f32_e32 v9, v9, v87
	v_mul_f32_e32 v10, v10, v90
	v_mul_f32_e32 v11, v11, v91
	v_cvt_pk_bf16_f32 v86, v8, v9
	v_cvt_pk_bf16_f32 v87, v10, v11
	ds_read_b128 v[8:11], v35
	s_mov_b32 s4, 0x3727c5ac
	s_add_u32 s0, s0, s75
	s_addc_u32 s1, s1, s77
	s_add_i32 s40, s40, s96
	s_waitcnt lgkmcnt(0)
	v_mov_b32_e32 v90, v9
	v_mov_b32_e32 v91, v10
	v_mov_b32_e32 v92, v8
	v_mov_b32_e32 v93, v11
	v_pk_add_f32 v[90:91], v[90:91], v[92:93]
	s_lshl_b64 s[0:1], s[0:1], 9
	v_add_f32_e32 v35, v90, v91
	s_cmpk_gt_i32 s40, 0x1ff
	s_waitcnt lgkmcnt(0)
	s_nop 1
	v_add_f32_dpp v35, v35, v35 quad_perm:[1,0,3,2] row_mask:0xf bank_mask:0xf
	s_waitcnt lgkmcnt(0)
	s_nop 1
	v_add_f32_dpp v35, v35, v35 quad_perm:[2,3,0,1] row_mask:0xf bank_mask:0xf
	s_waitcnt lgkmcnt(0)
	s_nop 1
	v_add_f32_dpp v35, v35, v35 row_half_mirror row_mask:0xf bank_mask:0xf
	s_waitcnt lgkmcnt(0)
	s_nop 1
	v_add_f32_dpp v35, v35, v35 row_mirror row_mask:0xf bank_mask:0xf
	ds_swizzle_b32 v90, v35 offset:swizzle(SWAP,16)
	s_waitcnt lgkmcnt(0)
	v_add_f32_e32 v35, v35, v90
	v_mov_b32_e32 v90, v35
	v_mov_b32_e32 v91, v35
	s_nop 1
	v_permlane32_swap_b32_e32 v90, v91
	v_add_u32_e32 v90, v90, v91
	v_sub_u32_e32 v90, v90, v35
	v_add_f32_e32 v35, v35, v90
	v_fmamk_f32 v9, v35, 0xbb800000, v9
	v_fmamk_f32 v8, v35, 0xbb800000, v8
	v_fmamk_f32 v11, v35, 0xbb800000, v11
	v_fmac_f32_e32 v10, 0xbb800000, v35
	v_pk_mul_f32 v[90:91], v[10:11], v[10:11]
	v_pk_mul_f32 v[92:93], v[8:9], v[8:9]
	s_nop 0
	v_pk_mov_b32 v[94:95], v[92:93], v[90:91] op_sel:[1,0]
	v_mov_b32_e32 v93, v91
	v_pk_add_f32 v[90:91], v[94:95], v[92:93]
	s_nop 0
	v_add_f32_e32 v35, v90, v91
	s_waitcnt lgkmcnt(0)
	s_nop 1
	v_add_f32_dpp v35, v35, v35 quad_perm:[1,0,3,2] row_mask:0xf bank_mask:0xf
	s_waitcnt lgkmcnt(0)
	s_nop 1
	v_add_f32_dpp v35, v35, v35 quad_perm:[2,3,0,1] row_mask:0xf bank_mask:0xf
	s_waitcnt lgkmcnt(0)
	s_nop 1
	v_add_f32_dpp v35, v35, v35 row_half_mirror row_mask:0xf bank_mask:0xf
	v_lshl_add_u64 v[90:91], v[12:13], 0, s[2:3]
	global_store_dwordx2 v[90:91], v[86:87], off
	s_waitcnt lgkmcnt(0)
	s_nop 1
	v_add_f32_dpp v35, v35, v35 row_mirror row_mask:0xf bank_mask:0xf
	ds_swizzle_b32 v92, v35 offset:swizzle(SWAP,16)
	v_mov_b32_e32 v86, s4
	s_waitcnt lgkmcnt(0)
	v_add_f32_e32 v35, v35, v92
	v_mov_b32_e32 v87, v35
	v_mov_b32_e32 v90, v35
	s_nop 1
	v_permlane32_swap_b32_e32 v87, v90
	v_add_u32_e32 v87, v87, v90
	v_sub_u32_e32 v87, v87, v35
	v_add_f32_e32 v35, v35, v87
	v_fmac_f32_e32 v86, 0x3b800000, v35
	v_rsq_f32_e32 v86, v86
	v_lshl_add_u64 v[90:91], v[12:13], 0, s[0:1]
	v_pk_mul_f32 v[8:9], v[8:9], v[86:87] op_sel_hi:[1,0]
	v_pk_mul_f32 v[10:11], v[10:11], v[86:87] op_sel_hi:[1,0]
	v_pk_fma_f32 v[0:1], v[0:1], v[8:9], v[4:5]
	v_pk_fma_f32 v[2:3], v[2:3], v[10:11], v[6:7]
	v_mul_f32_e32 v4, 0xbfb8aa3b, v0
	v_mul_f32_e32 v5, 0xbfb8aa3b, v1
	v_mul_f32_e32 v6, 0xbfb8aa3b, v2
	v_mul_f32_e32 v7, 0xbfb8aa3b, v3
	v_exp_f32_e32 v4, v4
	v_exp_f32_e32 v5, v5
	v_exp_f32_e32 v6, v6
	v_exp_f32_e32 v7, v7
	v_add_f32_e32 v4, 1.0, v4
	v_add_f32_e32 v5, 1.0, v5
	v_add_f32_e32 v6, 1.0, v6
	v_add_f32_e32 v7, 1.0, v7
	v_rcp_f32_e32 v4, v4
	v_rcp_f32_e32 v5, v5
	v_rcp_f32_e32 v6, v6
	v_rcp_f32_e32 v7, v7
	v_mul_f32_e32 v0, v0, v4
	v_mul_f32_e32 v1, v1, v5
	v_mul_f32_e32 v2, v2, v6
	v_mul_f32_e32 v3, v3, v7
	v_cvt_pk_bf16_f32 v0, v0, v1
	v_cvt_pk_bf16_f32 v1, v2, v3
	global_store_dwordx2 v[90:91], v[0:1], off
	s_barrier
	s_cbranch_scc0 .LBB0_101

; __device__ __forceinline__ unsigned cvt_pk_bf16(float lo, float hi) { unsigned r; asm volatile("v_cvt_pk_bf16_f32 %0, %1, %2" : "=v"(r) : "v"(lo), "v"(hi)); return r; }
; __device__ __forceinline__ float bf_lo(unsigned w) { return __uint_as_float(w << 16); }
; __device__ __forceinline__ float bf_hi(unsigned w) { return __uint_as_float(w & 0xffff0000u); }
; __device__ __forceinline__ float ln_eps_s() { float e = LN_EPS; asm volatile("" : "+s"(e)); return e; }
; __device__ __forceinline__ void ln_pass(const float* YF, float* OUT, const bf16_t* YB, bf16_t* XB, float* stats, const float* g, const float* b, bool final, int gw, int NGW, int lane) {
;     ...
;         for (int m = gw; m < MTOK; m += NGW) {
;             const u32x4* xr = (const u32x4*)(YB + (size_t)m * DM) + lane; u32x4* orow = (u32x4*)(XB + (size_t)m * DM) + lane;
;             const u32x4 r0 = xr[0], r1 = xr[64];
;             f32x4 v[4] = {{bf_lo(r0.x), bf_hi(r0.x), bf_lo(r0.y), bf_hi(r0.y)}, {bf_lo(r0.z), bf_hi(r0.z), bf_lo(r0.w), bf_hi(r0.w)},
;                           {bf_lo(r1.x), bf_hi(r1.x), bf_lo(r1.y), bf_hi(r1.y)}, {bf_lo(r1.z), bf_hi(r1.z), bf_lo(r1.w), bf_hi(r1.w)}};
;             float s = 0.f;
; #pragma unroll
;             for (int j = 0; j < 4; ++j) s += (v[j].x + v[j].y) + (v[j].z + v[j].w);
;             const float mean = wave_sum(s) * (1.f / DM); float s2 = 0.f;
; #pragma unroll
;             for (int j = 0; j < 4; ++j) { v[j] = v[j] - mean; s2 += (v[j].x * v[j].x + v[j].y * v[j].y) + (v[j].z * v[j].z + v[j].w * v[j].w); }
;             const float rstd = __builtin_amdgcn_rsqf(wave_sum(s2) * (1.f / DM) + ln_eps_s());
;             f32x4 o[4];
; #pragma unroll
;             for (int j = 0; j < 4; ++j) o[j] = v[j] * rstd * gg[j] + bb[j];
;             u32x4 w0, w1;
;             w0.x = cvt_pk_bf16(o[0].x, o[0].y); w0.y = cvt_pk_bf16(o[0].z, o[0].w); w0.z = cvt_pk_bf16(o[1].x, o[1].y); w0.w = cvt_pk_bf16(o[1].z, o[1].w);
;             w1.x = cvt_pk_bf16(o[2].x, o[2].y); w1.y = cvt_pk_bf16(o[2].z, o[2].w); w1.z = cvt_pk_bf16(o[3].x, o[3].y); w1.w = cvt_pk_bf16(o[3].z, o[3].w);
;             orow[0] = w0; orow[64] = w1;
;             if (lane == 0) *(f32x2*)(stats + (size_t)m * 2) = (f32x2){mean, rstd};
.LBB0_494:
	v_lshl_add_u64 v[34:35], s[14:15], 0, v[32:33]
	global_load_dwordx4 v[38:41], v[34:35], off
	global_load_dwordx4 v[48:51], v[34:35], off offset:-1024
	s_mov_b32 s16, 0x3727c5ac
	s_waitcnt vmcnt(1)
	v_lshlrev_b32_e32 v34, 16, v38
	s_waitcnt vmcnt(0)
	v_lshlrev_b32_e32 v45, 16, v49
	v_lshlrev_b32_e32 v44, 16, v48
	v_and_b32_e32 v53, 0xffff0000, v49
	v_and_b32_e32 v52, 0xffff0000, v48
	v_lshlrev_b32_e32 v49, 16, v51
	v_lshlrev_b32_e32 v48, 16, v50
	v_and_b32_e32 v51, 0xffff0000, v51
	v_and_b32_e32 v50, 0xffff0000, v50
	v_pk_add_f32 v[54:55], v[44:45], v[52:53]
	v_pk_add_f32 v[56:57], v[48:49], v[50:51]
	v_and_b32_e32 v35, 0xffff0000, v38
	v_lshlrev_b32_e32 v36, 16, v39
	v_and_b32_e32 v37, 0xffff0000, v39
	v_lshlrev_b32_e32 v38, 16, v40
	v_and_b32_e32 v42, 0xffff0000, v40
	v_lshlrev_b32_e32 v40, 16, v41
	v_and_b32_e32 v46, 0xffff0000, v41
	v_add_f32_e32 v41, v54, v55
	v_pk_add_f32 v[54:55], v[56:57], v[56:57] op_sel_hi:[0,1]
	v_add_f32_e32 v39, v34, v35
	v_add_f32_e32 v43, v36, v37
	v_add_f32_e32 v47, 0, v41
	v_mov_b32_e32 v41, v55
	v_pk_add_f32 v[56:57], v[38:39], v[42:43]
	v_pk_add_f32 v[54:55], v[40:41], v[46:47]
	v_mov_b32_e32 v47, s16
	v_pk_add_f32 v[54:55], v[56:57], v[54:55]
	s_nop 0
	v_add_f32_e32 v39, v54, v55
	s_waitcnt lgkmcnt(0)
	s_nop 1
	v_add_f32_dpp v39, v39, v39 quad_perm:[1,0,3,2] row_mask:0xf bank_mask:0xf
	s_waitcnt lgkmcnt(0)
	s_nop 1
	v_add_f32_dpp v39, v39, v39 quad_perm:[2,3,0,1] row_mask:0xf bank_mask:0xf
	s_waitcnt lgkmcnt(0)
	s_nop 1
	v_add_f32_dpp v39, v39, v39 row_half_mirror row_mask:0xf bank_mask:0xf
	s_waitcnt lgkmcnt(0)
	s_nop 1
	v_add_f32_dpp v39, v39, v39 row_mirror row_mask:0xf bank_mask:0xf
	ds_swizzle_b32 v41, v39 offset:swizzle(SWAP,16)
	s_waitcnt lgkmcnt(0)
	v_add_f32_e32 v39, v39, v41
	v_mov_b32_e32 v41, v39
	v_mov_b32_e32 v43, v39
	s_nop 1
	v_permlane32_swap_b32_e32 v41, v43
	v_add_u32_e32 v41, v41, v43
	v_sub_u32_e32 v41, v41, v39
	v_add_f32_e32 v43, v39, v41
	v_fmac_f32_e32 v52, 0xba800000, v43
	v_fmac_f32_e32 v53, 0xba800000, v43
	v_fmac_f32_e32 v45, 0xba800000, v43
	v_fmac_f32_e32 v50, 0xba800000, v43
	v_fmac_f32_e32 v51, 0xba800000, v43
	v_fmac_f32_e32 v49, 0xba800000, v43
	v_fmac_f32_e32 v44, 0xba800000, v43
	v_fmac_f32_e32 v48, 0xba800000, v43
	v_fmac_f32_e32 v34, 0xba800000, v43
	v_fmac_f32_e32 v36, 0xba800000, v43
	v_mov_b32_e32 v54, v45
	v_mov_b32_e32 v55, v53
	v_mov_b32_e32 v45, v52
	v_mov_b32_e32 v52, v49
	v_mov_b32_e32 v53, v51
	v_mov_b32_e32 v49, v50
	v_fmac_f32_e32 v35, 0xba800000, v43
	v_fmac_f32_e32 v37, 0xba800000, v43
	v_mul_f32_e32 v50, v34, v34
	v_mul_f32_e32 v56, v36, v36
	v_pk_mul_f32 v[58:59], v[54:55], v[54:55]
	v_pk_mul_f32 v[60:61], v[44:45], v[44:45]
	v_pk_mul_f32 v[62:63], v[52:53], v[52:53]
	v_pk_mul_f32 v[64:65], v[48:49], v[48:49]
	v_fmac_f32_e32 v42, 0xba800000, v43
	v_fmac_f32_e32 v38, 0xba800000, v43
	v_pk_fma_f32 v[50:51], v[34:35], v[34:35], v[50:51] op_sel_hi:[1,1,0]
	v_pk_fma_f32 v[56:57], v[36:37], v[36:37], v[56:57] op_sel_hi:[1,1,0]
	v_pk_mov_b32 v[66:67], v[60:61], v[58:59] op_sel:[1,0]
	v_mov_b32_e32 v61, v59
	v_pk_mov_b32 v[58:59], v[64:65], v[62:63] op_sel:[1,0]
	v_mov_b32_e32 v65, v63
	v_mul_f32_e32 v50, v38, v38
	v_mul_f32_e32 v56, v42, v42
	v_pk_add_f32 v[60:61], v[66:67], v[60:61]
	v_pk_add_f32 v[58:59], v[58:59], v[64:65]
	v_fmac_f32_e32 v46, 0xba800000, v43
	v_fmac_f32_e32 v40, 0xba800000, v43
	v_pk_add_f32 v[50:51], v[50:51], v[56:57]
	v_pk_add_f32 v[56:57], v[60:61], v[60:61] op_sel_hi:[0,1]
	v_pk_add_f32 v[58:59], v[58:59], v[58:59] op_sel_hi:[0,1]
	v_mul_f32_e32 v56, v40, v40
	v_mul_f32_e32 v58, v46, v46
	v_pk_add_f32 v[56:57], v[56:57], v[58:59]
	s_nop 0
	v_pk_add_f32 v[50:51], v[50:51], v[56:57]
	s_nop 0
	v_add_f32_e32 v39, v50, v51
	v_lshl_add_u64 v[50:51], s[28:29], 0, v[32:33]
	v_add_co_u32_e32 v56, vcc, 0x6400000, v50
	s_waitcnt lgkmcnt(0)
	s_nop 1
	v_add_f32_dpp v39, v39, v39 quad_perm:[1,0,3,2] row_mask:0xf bank_mask:0xf
	v_addc_co_u32_e32 v57, vcc, 0, v51, vcc
	s_waitcnt lgkmcnt(0)
	s_nop 1
	v_add_f32_dpp v39, v39, v39 quad_perm:[2,3,0,1] row_mask:0xf bank_mask:0xf
	s_waitcnt lgkmcnt(0)
	s_nop 1
	v_add_f32_dpp v39, v39, v39 row_half_mirror row_mask:0xf bank_mask:0xf
	s_waitcnt lgkmcnt(0)
	s_nop 1
	v_add_f32_dpp v39, v39, v39 row_mirror row_mask:0xf bank_mask:0xf
	ds_swizzle_b32 v41, v39 offset:swizzle(SWAP,16)
	s_waitcnt lgkmcnt(0)
	v_add_f32_e32 v39, v39, v41
	v_mov_b32_e32 v41, v39
	v_mov_b32_e32 v50, v39
	s_nop 1
	v_permlane32_swap_b32_e32 v41, v50
	v_add_u32_e32 v41, v41, v50
	v_sub_u32_e32 v41, v41, v39
	v_add_f32_e32 v39, v39, v41
	v_fmac_f32_e32 v47, 0x3a800000, v39
	v_rsq_f32_e32 v50, v47
	v_mov_b32_e32 v39, v42
	v_mov_b32_e32 v41, v46
	v_pk_mul_f32 v[44:45], v[44:45], v[50:51] op_sel_hi:[1,0]
	v_pk_mul_f32 v[46:47], v[54:55], v[50:51] op_sel_hi:[1,0]
	v_pk_mul_f32 v[48:49], v[48:49], v[50:51] op_sel_hi:[1,0]
	v_pk_mul_f32 v[52:53], v[52:53], v[50:51] op_sel_hi:[1,0]
	v_pk_mul_f32 v[34:35], v[34:35], v[50:51] op_sel_hi:[1,0]
	v_pk_mul_f32 v[36:37], v[36:37], v[50:51] op_sel_hi:[1,0]
	v_pk_mul_f32 v[38:39], v[38:39], v[50:51] op_sel_hi:[1,0]
	v_pk_mul_f32 v[40:41], v[40:41], v[50:51] op_sel_hi:[1,0]
	v_pk_fma_f32 v[46:47], v[6:7], v[46:47], v[14:15]
	v_pk_fma_f32 v[44:45], v[4:5], v[44:45], v[12:13]
	v_pk_fma_f32 v[52:53], v[2:3], v[52:53], v[10:11]
	v_pk_fma_f32 v[48:49], v[0:1], v[48:49], v[8:9]
	v_pk_fma_f32 v[54:55], v[22:23], v[36:37], v[30:31]
	v_pk_fma_f32 v[58:59], v[20:21], v[34:35], v[28:29]
	v_pk_fma_f32 v[60:61], v[18:19], v[40:41], v[26:27]
	v_pk_fma_f32 v[40:41], v[16:17], v[38:39], v[24:25]
	v_cvt_pk_bf16_f32 v34, v44, v45
	v_cvt_pk_bf16_f32 v35, v46, v47
	v_cvt_pk_bf16_f32 v36, v48, v49
	v_cvt_pk_bf16_f32 v37, v52, v53
	v_cvt_pk_bf16_f32 v38, v58, v59
	v_cvt_pk_bf16_f32 v39, v54, v55
	s_nop 0
	v_cvt_pk_bf16_f32 v40, v40, v41
	v_cvt_pk_bf16_f32 v41, v60, v61
	global_store_dwordx4 v[56:57], v[34:37], off
	global_store_dwordx4 v[56:57], v[38:41], off offset:1024
	s_and_saveexec_b64 s[16:17], s[4:5]
	s_cbranch_execz .LBB0_493
	v_mul_f32_e32 v34, 0x3a800000, v43
	v_mov_b32_e32 v35, v50
	global_store_dwordx2 v235, v[34:35], s[8:9]
	s_branch .LBB0_493

; __device__ __forceinline__ float ln_eps_s() { float e = LN_EPS; asm volatile("" : "+s"(e)); return e; }
; __device__ __forceinline__ void ln_pass(const float* YF, float* OUT, const bf16_t* YB, bf16_t* XB, float* stats, const float* g, const float* b, bool final, int gw, int NGW, int lane) {
;     ...
;         for (int m = gw; m < MTOK; m += NGW) {
;             const f32x4* xr = (const f32x4*)(YF + (size_t)m * DM) + lane; f32x4* orow = (f32x4*)(OUT + (size_t)m * DM) + lane;
;             f32x4 v[4]; float s = 0.f;
; #pragma unroll
;             for (int j = 0; j < 4; ++j) { v[j] = xr[64 * j]; s += (v[j].x + v[j].y) + (v[j].z + v[j].w); }
;             const float mean = wave_sum(s) * (1.f / DM); float s2 = 0.f;
; #pragma unroll
;             for (int j = 0; j < 4; ++j) { v[j] = v[j] - mean; s2 += (v[j].x * v[j].x + v[j].y * v[j].y) + (v[j].z * v[j].z + v[j].w * v[j].w); }
;             const float rstd = __builtin_amdgcn_rsqf(wave_sum(s2) * (1.f / DM) + ln_eps_s());
; #pragma unroll
;             for (int j = 0; j < 4; ++j) orow[64 * j] = v[j] * rstd * gg[j] + bb[j];
;         }
.LBB0_500:
	v_lshl_add_u64 v[32:33], s[2:3], 0, v[234:235]
	v_add_co_u32_e32 v50, vcc, 0x18000000, v32
	s_mov_b32 s6, 0x3727c5ac
	s_nop 0
	v_addc_co_u32_e32 v51, vcc, 0, v33, vcc
	global_load_dwordx4 v[44:47], v[50:51], off
	global_load_dwordx4 v[40:43], v[50:51], off offset:1024
	global_load_dwordx4 v[32:35], v[50:51], off offset:2048
	global_load_dwordx4 v[36:39], v[50:51], off offset:3072
	s_add_i32 s62, s62, s64
	v_mov_b32_e32 v64, s6
	s_add_u32 s2, s2, s4
	s_addc_u32 s3, s3, s5
	v_lshl_add_u64 v[48:49], s[0:1], 0, v[234:235]
	s_add_u32 s0, s0, s4
	s_addc_u32 s1, s1, s5
	s_cmpk_gt_i32 s62, 0x7fff
	s_waitcnt vmcnt(3)
	v_mov_b32_e32 v50, v45
	v_mov_b32_e32 v51, v46
	v_mov_b32_e32 v52, v44
	v_mov_b32_e32 v53, v47
	s_waitcnt vmcnt(2)
	v_mov_b32_e32 v54, v41
	v_mov_b32_e32 v55, v42
	v_mov_b32_e32 v56, v40
	v_mov_b32_e32 v57, v43
	v_pk_add_f32 v[50:51], v[50:51], v[52:53]
	v_pk_add_f32 v[52:53], v[54:55], v[56:57]
	v_add_f32_e32 v56, v50, v51
	v_pk_add_f32 v[50:51], v[52:53], v[52:53] op_sel:[0,1] op_sel_hi:[1,0]
	s_waitcnt vmcnt(1)
	v_add_f32_e32 v58, v32, v33
	v_add_f32_e32 v60, v34, v35
	s_waitcnt vmcnt(0)
	v_mov_b32_e32 v63, v36
	v_mov_b32_e32 v59, v38
	v_mov_b32_e32 v61, v39
	v_add_f32_e32 v62, 0, v56
	v_mov_b32_e32 v51, v37
	v_pk_add_f32 v[54:55], v[58:59], v[60:61]
	v_pk_add_f32 v[50:51], v[62:63], v[50:51]
	s_nop 0
	v_pk_add_f32 v[50:51], v[50:51], v[54:55]
	s_nop 0
	v_add_f32_e32 v50, v50, v51
	s_waitcnt lgkmcnt(0)
	s_nop 1
	v_add_f32_dpp v50, v50, v50 quad_perm:[1,0,3,2] row_mask:0xf bank_mask:0xf
	s_waitcnt lgkmcnt(0)
	s_nop 1
	v_add_f32_dpp v50, v50, v50 quad_perm:[2,3,0,1] row_mask:0xf bank_mask:0xf
	s_waitcnt lgkmcnt(0)
	s_nop 1
	v_add_f32_dpp v50, v50, v50 row_half_mirror row_mask:0xf bank_mask:0xf
	s_waitcnt lgkmcnt(0)
	s_nop 1
	v_add_f32_dpp v50, v50, v50 row_mirror row_mask:0xf bank_mask:0xf
	ds_swizzle_b32 v51, v50 offset:swizzle(SWAP,16)
	s_waitcnt lgkmcnt(0)
	v_add_f32_e32 v50, v50, v51
	v_mov_b32_e32 v51, v50
	v_mov_b32_e32 v52, v50
	s_nop 1
	v_permlane32_swap_b32_e32 v51, v52
	v_add_u32_e32 v51, v51, v52
	v_sub_u32_e32 v51, v51, v50
	v_add_f32_e32 v50, v50, v51
	v_fmamk_f32 v45, v50, 0xba800000, v45
	v_fmamk_f32 v44, v50, 0xba800000, v44
	v_fmamk_f32 v47, v50, 0xba800000, v47
	v_fmac_f32_e32 v46, 0xba800000, v50
	v_fmamk_f32 v41, v50, 0xba800000, v41
	v_fmamk_f32 v40, v50, 0xba800000, v40
	v_fmamk_f32 v43, v50, 0xba800000, v43
	v_fmac_f32_e32 v42, 0xba800000, v50
	v_fmamk_f32 v33, v50, 0xba800000, v33
	v_fmamk_f32 v32, v50, 0xba800000, v32
	v_fmamk_f32 v35, v50, 0xba800000, v35
	v_fmac_f32_e32 v34, 0xba800000, v50
	v_fmamk_f32 v37, v50, 0xba800000, v37
	v_fmac_f32_e32 v36, 0xba800000, v50
	v_fmamk_f32 v39, v50, 0xba800000, v39
	v_fmamk_f32 v38, v50, 0xba800000, v38
	v_pk_mul_f32 v[50:51], v[46:47], v[46:47]
	v_pk_mul_f32 v[52:53], v[44:45], v[44:45]
	v_pk_mul_f32 v[54:55], v[42:43], v[42:43]
	v_pk_mul_f32 v[56:57], v[40:41], v[40:41]
	v_pk_mov_b32 v[62:63], v[52:53], v[50:51] op_sel:[1,0]
	v_mov_b32_e32 v53, v51
	v_pk_mov_b32 v[50:51], v[56:57], v[54:55] op_sel:[1,0]
	v_mov_b32_e32 v57, v55
	v_mul_f32_e32 v58, v32, v32
	v_mul_f32_e32 v60, v34, v34
	v_pk_add_f32 v[52:53], v[62:63], v[52:53]
	v_pk_add_f32 v[50:51], v[50:51], v[56:57]
	v_pk_fma_f32 v[54:55], v[32:33], v[32:33], v[58:59] op_sel_hi:[1,1,0]
	v_pk_fma_f32 v[58:59], v[34:35], v[34:35], v[60:61] op_sel_hi:[1,1,0]
	v_pk_add_f32 v[52:53], v[52:53], v[52:53] op_sel_hi:[0,1]
	v_pk_add_f32 v[50:51], v[50:51], v[50:51] op_sel_hi:[0,1]
	v_mul_f32_e32 v54, v36, v36
	v_mul_f32_e32 v58, v37, v37
	v_mul_f32_e32 v52, v38, v38
	v_mul_f32_e32 v50, v39, v39
	v_pk_add_f32 v[54:55], v[54:55], v[58:59]
	v_pk_add_f32 v[50:51], v[52:53], v[50:51]
	s_nop 0
	v_pk_add_f32 v[50:51], v[54:55], v[50:51]
	s_nop 0
	v_add_f32_e32 v50, v50, v51
	s_waitcnt lgkmcnt(0)
	s_nop 1
	v_add_f32_dpp v50, v50, v50 quad_perm:[1,0,3,2] row_mask:0xf bank_mask:0xf
	s_waitcnt lgkmcnt(0)
	s_nop 1
	v_add_f32_dpp v50, v50, v50 quad_perm:[2,3,0,1] row_mask:0xf bank_mask:0xf
	s_waitcnt lgkmcnt(0)
	s_nop 1
	v_add_f32_dpp v50, v50, v50 row_half_mirror row_mask:0xf bank_mask:0xf
	s_waitcnt lgkmcnt(0)
	s_nop 1
	v_add_f32_dpp v50, v50, v50 row_mirror row_mask:0xf bank_mask:0xf
	ds_swizzle_b32 v51, v50 offset:swizzle(SWAP,16)
	s_waitcnt lgkmcnt(0)
	v_add_f32_e32 v50, v50, v51
	v_mov_b32_e32 v51, v50
	v_mov_b32_e32 v52, v50
	s_nop 1
	v_permlane32_swap_b32_e32 v51, v52
	v_add_u32_e32 v51, v51, v52
	v_sub_u32_e32 v51, v51, v50
	v_add_f32_e32 v50, v50, v51
	v_fmac_f32_e32 v64, 0x3a800000, v50
	v_rsq_f32_e32 v50, v64
	s_nop 0
	v_pk_mul_f32 v[44:45], v[44:45], v[50:51] op_sel_hi:[1,0]
	v_pk_mul_f32 v[46:47], v[46:47], v[50:51] op_sel_hi:[1,0]
	v_pk_mul_f32 v[40:41], v[40:41], v[50:51] op_sel_hi:[1,0]
	v_pk_mul_f32 v[42:43], v[42:43], v[50:51] op_sel_hi:[1,0]
	v_pk_mul_f32 v[52:53], v[32:33], v[50:51] op_sel_hi:[1,0]
	v_pk_mul_f32 v[54:55], v[34:35], v[50:51] op_sel_hi:[1,0]
	v_pk_mul_f32 v[56:57], v[36:37], v[50:51] op_sel_hi:[1,0]
	v_pk_mul_f32 v[50:51], v[38:39], v[50:51] op_sel_hi:[1,0]
	v_pk_fma_f32 v[34:35], v[2:3], v[46:47], v[10:11]
	v_pk_fma_f32 v[32:33], v[0:1], v[44:45], v[8:9]
	v_pk_fma_f32 v[38:39], v[6:7], v[42:43], v[14:15]
	v_pk_fma_f32 v[36:37], v[4:5], v[40:41], v[12:13]
	v_pk_fma_f32 v[42:43], v[18:19], v[54:55], v[26:27]
	v_pk_fma_f32 v[40:41], v[16:17], v[52:53], v[24:25]
	v_pk_fma_f32 v[46:47], v[22:23], v[50:51], v[30:31]
	v_pk_fma_f32 v[44:45], v[20:21], v[56:57], v[28:29]
	global_store_dwordx4 v[48:49], v[32:35], off
	global_store_dwordx4 v[48:49], v[36:39], off offset:1024
	global_store_dwordx4 v[48:49], v[40:43], off offset:2048
	global_store_dwordx4 v[48:49], v[44:47], off offset:3072
	s_cbranch_scc0 .LBB0_500
